# attention tile loops: XNACK-replay s_nop 0 between back-to-back loads removed (xnack- target), 21 sites
# baseline (speedup 1.0000x reference)
; #define LAS __attribute__((address_space(3)))
; #define MFMA32(a, b, c) __builtin_amdgcn_mfma_f32_32x32x16_bf16((a), (b), (c), 0, 0, 0)
; DI f32x16 zero16() { f32x16 z; for (int i = 0; i < 16; ++i) z[i] = 0.f; return z; }
; DI int tsw(int row) { return ((row >> 4) & 3) << 3; }
; template <class F> DI void load_v(u32x4 (&vr)[8], int lane, F vrow) {
; #pragma unroll
;     for (int it = 0; it < 8; ++it) { const int id = it * 64 + lane, key = id >> 3, part = id & 7; vr[it] = *(const u32x4*)(vrow(key) + 8 * part); }
; }
; DI void put_vt(LAS bf16_t* Vt, int lane, const u32x4 (&vr)[8]) {
; #pragma unroll
;     for (int it = 0; it < 8; ++it) { const int id = it * 64 + lane, key = id >> 3, part = id & 7; const u32x4 w = vr[it];
; #pragma unroll
;         for (int j = 0; j < 4; ++j) { const int d0 = 8 * part + 2 * j, ks_ = key ^ tsw(d0); Vt[d0 * TLD + ks_] = (bf16_t)(w[j] & 0xffffu); Vt[(d0 + 1) * TLD + ks_] = (bf16_t)(w[j] >> 16); } }
; }
; DI void na_wave_unit(KArgs args, LAS unsigned char* L, const Ctx& c, int u, int lane, int wave) {
;     ...
;     for (int w = 0; w < 8; ++w) {
;         const size_t tk0 = (size_t)seq * c.seqlen + (size_t)(rs + w) * 64;
;         u32x4 vr[8]; bf16x8 kf[2][4];
;         load_v(vr, lane, [&](int key) { return PROJ + (tk0 + key) * NPROJ + C_VA + 64 * head; });
; #pragma unroll
;         for (int mt = 0; mt < 2; ++mt)
; #pragma unroll
;             for (int ks = 0; ks < 4; ++ks) kf[mt][ks] = *(const bf16x8*)(PROJ + (tk0 + 32 * mt + rr) * NPROJ + C_KA + 64 * head + 16 * ks + 8 * hh);
;         __builtin_amdgcn_sched_barrier(0);
;         asm volatile("s_waitcnt lgkmcnt(0)" ::: "memory");
;         put_vt(Vt, lane, vr);
;         f32x16 acc[2][2]; acc[0][0] = zero16(); acc[0][1] = zero16(); acc[1][0] = zero16(); acc[1][1] = zero16();
; #pragma unroll
;         for (int mt = 0; mt < 2; ++mt)
; #pragma unroll
;             for (int ks = 0; ks < 4; ++ks) { acc[mt][0] = MFMA32(kf[mt][ks], qf[0][ks], acc[mt][0]); acc[mt][1] = MFMA32(kf[mt][ks], qf[1][ks], acc[mt][1]); }
.LBB0_661:
	s_ashr_i32 s3, s2, 31
	s_lshl_b64 vcc, s[2:3], 6
	s_add_u32 s3, vcc_lo, s94
	v_or_b32_e32 v68, s3, v182
	s_addc_u32 s5, vcc_hi, s95
	v_mad_u64_u32 v[72:73], vcc, v68, s90, v[204:205]
	v_or_b32_e32 v68, s3, v184
	v_mad_u64_u32 v[76:77], vcc, v68, s90, v[204:205]
	v_or_b32_e32 v68, s3, v186
	v_mad_u64_u32 v[80:81], vcc, v68, s90, v[204:205]
	v_or_b32_e32 v68, s3, v188
	s_waitcnt vmcnt(0)
	v_mad_u64_u32 v[100:101], vcc, v68, s90, v[204:205]
	v_or_b32_e32 v68, s3, v190
	v_mad_u64_u32 v[104:105], vcc, v68, s90, v[204:205]
	v_or_b32_e32 v68, s3, v192
	v_mad_u64_u32 v[108:109], vcc, v68, s90, v[204:205]
	v_or_b32_e32 v68, s3, v194
	v_mad_u64_u32 v[112:113], vcc, v68, s90, v[204:205]
	v_or_b32_e32 v68, s3, v196
	v_mad_u64_u32 v[116:117], vcc, v68, s90, v[204:205]
	v_or_b32_e32 v70, s3, v176
	v_mov_b64_e32 v[68:69], s[6:7]
	v_mad_u64_u32 v[68:69], vcc, v70, s90, v[68:69]
	v_mad_i32_i24 v69, s5, v223, v69
	s_lshl_b32 s92, s33, 1
	v_lshl_add_u64 v[68:69], v[68:69], 0, s[92:93]
	v_lshl_add_u64 v[74:75], v[68:69], 0, v[2:3]
	s_mov_b64 vcc, 0x38200
	global_load_dwordx4 v[68:71], v[74:75], off offset:512
	global_load_dwordx4 v[88:91], v[74:75], off offset:544
	global_load_dwordx4 v[92:95], v[74:75], off offset:576
	global_load_dwordx4 v[96:99], v[74:75], off offset:608
	v_lshl_add_u64 v[78:79], v[74:75], 0, vcc
	v_add_co_u32_e32 v74, vcc, s0, v74
	v_mad_i32_i24 v73, s5, v223, v73
	v_mad_i32_i24 v77, s5, v223, v77
	v_mad_i32_i24 v81, s5, v223, v81
	v_mad_i32_i24 v101, s5, v223, v101
	v_mad_i32_i24 v105, s5, v223, v105
	v_mad_i32_i24 v109, s5, v223, v109
	v_mad_i32_i24 v113, s5, v223, v113
	v_mad_i32_i24 v117, s5, v223, v117
	v_addc_co_u32_e32 v75, vcc, 0, v75, vcc
	global_load_dwordx4 v[172:175], v[78:79], off offset:32
	global_load_dwordx4 v[164:167], v[78:79], off offset:64
	global_load_dwordx4 v[84:87], v[74:75], off offset:512
	global_load_dwordx4 v[168:171], v[78:79], off offset:96
	global_load_dwordx4 v[72:75], v[72:73], off offset:1024
	global_load_dwordx4 v[76:79], v[76:77], off offset:1024
	global_load_dwordx4 v[80:83], v[80:81], off offset:1024
	global_load_dwordx4 v[100:103], v[100:101], off offset:1024
	global_load_dwordx4 v[104:107], v[104:105], off offset:1024
	global_load_dwordx4 v[108:111], v[108:109], off offset:1024
	global_load_dwordx4 v[112:115], v[112:113], off offset:1024
	global_load_dwordx4 v[116:119], v[116:117], off offset:1024
	s_waitcnt lgkmcnt(0)
	s_waitcnt vmcnt(7)
	ds_write_b16 v189, v72
	ds_write_b16_d16_hi v189, v72 offset:144
	ds_write_b16 v189, v73 offset:288
	ds_write_b16_d16_hi v189, v73 offset:432
	ds_write_b16 v189, v74 offset:576
	ds_write_b16_d16_hi v189, v74 offset:720
	ds_write_b16 v189, v75 offset:864
	ds_write_b16_d16_hi v189, v75 offset:1008
	s_waitcnt vmcnt(6)
	ds_write_b16 v191, v76
	ds_write_b16_d16_hi v191, v76 offset:144
	ds_write_b16 v191, v77 offset:288
	ds_write_b16_d16_hi v191, v77 offset:432
	ds_write_b16 v191, v78 offset:576
	ds_write_b16_d16_hi v191, v78 offset:720
	ds_write_b16 v191, v79 offset:864
	ds_write_b16_d16_hi v191, v79 offset:1008
	s_waitcnt vmcnt(5)
	ds_write_b16 v193, v80
	ds_write_b16_d16_hi v193, v80 offset:144
	ds_write_b16 v193, v81 offset:288
	ds_write_b16_d16_hi v193, v81 offset:432
	ds_write_b16 v193, v82 offset:576
	ds_write_b16_d16_hi v193, v82 offset:720
	ds_write_b16 v193, v83 offset:864
	ds_write_b16_d16_hi v193, v83 offset:1008
	s_waitcnt vmcnt(4)
	ds_write_b16 v195, v100
	ds_write_b16_d16_hi v195, v100 offset:144
	ds_write_b16 v195, v101 offset:288
	ds_write_b16_d16_hi v195, v101 offset:432
	ds_write_b16 v195, v102 offset:576
	ds_write_b16_d16_hi v195, v102 offset:720
	ds_write_b16 v195, v103 offset:864
	ds_write_b16_d16_hi v195, v103 offset:1008
	s_waitcnt vmcnt(3)
	ds_write_b16 v189, v104 offset:64
	ds_write_b16_d16_hi v189, v104 offset:208
	ds_write_b16 v189, v105 offset:352
	ds_write_b16_d16_hi v189, v105 offset:496
	ds_write_b16 v189, v106 offset:640
	ds_write_b16_d16_hi v189, v106 offset:784
	ds_write_b16 v189, v107 offset:928
	ds_write_b16_d16_hi v189, v107 offset:1072
	s_waitcnt vmcnt(2)
	ds_write_b16 v197, v108
	ds_write_b16_d16_hi v197, v108 offset:144
	ds_write_b16 v197, v109 offset:288
	ds_write_b16_d16_hi v197, v109 offset:432
	ds_write_b16 v197, v110 offset:576
	ds_write_b16_d16_hi v197, v110 offset:720
	ds_write_b16 v197, v111 offset:864
	ds_write_b16_d16_hi v197, v111 offset:1008
	s_waitcnt vmcnt(1)
	ds_write_b16 v226, v112
	ds_write_b16_d16_hi v226, v112 offset:144
	ds_write_b16 v226, v113 offset:288
	ds_write_b16_d16_hi v226, v113 offset:432
	ds_write_b16 v226, v114 offset:576
	ds_write_b16_d16_hi v226, v114 offset:720
	ds_write_b16 v226, v115 offset:864
	ds_write_b16_d16_hi v226, v115 offset:1008
	s_waitcnt vmcnt(0)
	ds_write_b16 v227, v116
	ds_write_b16_d16_hi v227, v116 offset:144
	ds_write_b16 v227, v117 offset:288
	ds_write_b16_d16_hi v227, v117 offset:432
	ds_write_b16 v227, v118 offset:576
	ds_write_b16_d16_hi v227, v118 offset:720
	ds_write_b16 v227, v119 offset:864
	ds_write_b16_d16_hi v227, v119 offset:1008
	v_mfma_f32_32x32x16_bf16 v[100:115], v[68:71], v[132:135], 0
	s_waitcnt lgkmcnt(0)
; #define LAS __attribute__((address_space(3)))
; #define MFMA32(a, b, c) __builtin_amdgcn_mfma_f32_32x32x16_bf16((a), (b), (c), 0, 0, 0)
; DI int crow(int reg, int h) { return (reg & 3) + 8 * (reg >> 2) + 4 * h; }
; DI void osm_update(f32x16 (&acc)[2][2], f32x16 (&o)[2][2], float (&m)[2], float (&l)[2]) {
;     ...
;     for (int nt = 0; nt < 2; ++nt) { float mx = -1e30f;
; #pragma unroll
;         for (int mt = 0; mt < 2; ++mt)
; #pragma unroll
;             for (int g = 0; g < 16; ++g) mx = fmaxf(mx, acc[mt][nt][g]);
;         mx = fmaxf(mx, __shfl_xor(mx, 32));
; DI void na_wave_unit(KArgs args, LAS unsigned char* L, const Ctx& c, int u, int lane, int wave) {
;     ...
; #pragma unroll
;         for (int mt = 0; mt < 2; ++mt)
; #pragma unroll
;             for (int ks = 0; ks < 4; ++ks) { acc[mt][0] = MFMA32(kf[mt][ks], qf[0][ks], acc[mt][0]); acc[mt][1] = MFMA32(kf[mt][ks], qf[1][ks], acc[mt][1]); }
;         asm volatile("s_waitcnt lgkmcnt(0)" ::: "memory");
;         const LAS float* brow = BIAS + w * 32;
; #pragma unroll
;         for (int nt = 0; nt < 2; ++nt) { const int qc = 32 * nt + rr; int ws = qc - 8; ws = ws < 0 ? 0 : (ws > 48 ? 48 : ws);
; #pragma unroll
;             for (int mt = 0; mt < 2; ++mt) {
;                 const volatile LAS float* bp = brow + (32 * mt + 4 * hh - qc + 15); float bv[16];
; #pragma unroll
;                 for (int g = 0; g < 16; ++g) { const bool live = (mt == nt) || (nt == 0 ? g < 4 : g >= 12);
;                     bv[g] = live ? bp[(g & 3) + 8 * (g >> 2)] : 0.f; }
; #pragma unroll
;                 for (int g = 0; g < 16; ++g) { const bool live = (mt == nt) || (nt == 0 ? g < 4 : g >= 12); const int kc = 32 * mt + crow(g, hh); const bool ok = live && (kc >= ws) && (kc < ws + 16);
;                     acc[mt][nt][g] = ok ? acc[mt][nt][g] * 0.125f + bv[g] : -1e30f; } } }
	s_add_i32 s2, s2, 1
	v_mfma_f32_32x32x16_bf16 v[68:83], v[68:71], v[148:151], 0
	v_mfma_f32_32x32x16_bf16 v[100:115], v[88:91], v[136:139], v[100:115]
	v_mfma_f32_32x32x16_bf16 v[68:83], v[88:91], v[152:155], v[68:83]
	v_mfma_f32_32x32x16_bf16 v[116:131], v[84:87], v[132:135], 0
	v_mfma_f32_32x32x16_bf16 v[100:115], v[92:95], v[140:143], v[100:115]
	v_mfma_f32_32x32x16_bf16 v[68:83], v[92:95], v[156:159], v[68:83]
	v_mfma_f32_32x32x16_bf16 v[116:131], v[172:175], v[136:139], v[116:131]
	v_mfma_f32_32x32x16_bf16 v[100:115], v[96:99], v[144:147], v[100:115]
	v_mfma_f32_32x32x16_bf16 v[68:83], v[96:99], v[160:163], v[68:83]
	v_mfma_f32_32x32x16_bf16 v[84:99], v[84:87], v[148:151], 0
	s_nop 10
	v_add_u32_e32 v68, s4, v241
	v_mfma_f32_32x32x16_bf16 v[116:131], v[164:167], v[140:143], v[116:131]
	v_mfma_f32_32x32x16_bf16 v[84:99], v[172:175], v[152:155], v[84:99]
	v_mfma_f32_32x32x16_bf16 v[116:131], v[168:171], v[144:147], v[116:131]
	ds_read_b32 v69, v68
	ds_read_b32 v70, v68 offset:4
	ds_read_b32 v71, v68 offset:8
	ds_read_b32 v72, v68 offset:12
	ds_read_b32 v73, v68 offset:32
	ds_read_b32 v74, v68 offset:36
	ds_read_b32 v75, v68 offset:40
	ds_read_b32 v76, v68 offset:44
	ds_read_b32 v77, v68 offset:64
	ds_read_b32 v78, v68 offset:68
	s_nop 1
	ds_read_b32 v124, v68 offset:72
	ds_read_b32 v125, v68 offset:76
	ds_read_b32 v126, v68 offset:96
	ds_read_b32 v127, v68 offset:100
	ds_read_b32 v128, v68 offset:104
	ds_read_b32 v129, v68 offset:108
	s_waitcnt lgkmcnt(14)
	v_fmac_f32_e32 v70, 0x3e000000, v101
	s_waitcnt lgkmcnt(12)
	v_fmac_f32_e32 v72, 0x3e000000, v103
	v_cndmask_b32_e64 v122, v70, v224, s[18:19]
	v_cndmask_b32_e64 v120, v72, v224, s[22:23]
	s_waitcnt lgkmcnt(10)
	v_fmac_f32_e32 v74, 0x3e000000, v105
	ds_read_b32 v70, v68 offset:128
	ds_read_b32 v72, v68 offset:132
	ds_read_b32 v105, v68 offset:136
	ds_read_b32 v68, v68 offset:140
	v_mfma_f32_32x32x16_bf16 v[84:99], v[164:167], v[156:159], v[84:99]
	s_waitcnt lgkmcnt(12)
	v_fmac_f32_e32 v76, 0x3e000000, v107
	s_waitcnt lgkmcnt(3)
	v_fmac_f32_e32 v70, 0x3e000000, v116
	v_cndmask_b32_e64 v101, v76, v224, s[30:31]
	s_waitcnt lgkmcnt(0)
	v_fmac_f32_e32 v68, 0x3e000000, v119
	v_cndmask_b32_e64 v76, v224, v70, s[50:51]
	v_fmac_f32_e32 v72, 0x3e000000, v117
	v_fmac_f32_e32 v105, 0x3e000000, v118
	v_cndmask_b32_e64 v70, v224, v68, s[56:57]
	v_add_u32_e32 v68, s4, v240
	v_cndmask_b32_e64 v103, v74, v224, s[26:27]
	v_fmac_f32_e32 v75, 0x3e000000, v106
	v_fmac_f32_e32 v77, 0x3e000000, v108
	v_cndmask_b32_e64 v74, v224, v72, s[52:53]
	v_cndmask_b32_e64 v72, v224, v105, s[54:55]
	ds_read_b32 v105, v68
	ds_read_b32 v106, v68 offset:4
	ds_read_b32 v107, v68 offset:8
	ds_read_b32 v108, v68 offset:12
	v_mfma_f32_32x32x16_bf16 v[84:99], v[168:171], v[160:163], v[84:99]
	s_waitcnt lgkmcnt(3)
	v_fmac_f32_e32 v105, 0x3e000000, v80
	v_fmac_f32_e32 v78, 0x3e000000, v109
	s_waitcnt lgkmcnt(1)
	v_fmac_f32_e32 v107, 0x3e000000, v82
	s_waitcnt lgkmcnt(0)
	v_fmac_f32_e32 v108, 0x3e000000, v83
	v_fmac_f32_e32 v124, 0x3e000000, v110
	v_fmac_f32_e32 v125, 0x3e000000, v111
	v_fmac_f32_e32 v126, 0x3e000000, v112
	v_fmac_f32_e32 v127, 0x3e000000, v113
	v_fmac_f32_e32 v128, 0x3e000000, v114
	v_fmac_f32_e32 v129, 0x3e000000, v115
	v_cndmask_b32_e64 v110, v105, v224, s[58:59]
	v_fmac_f32_e32 v106, 0x3e000000, v81
	v_cndmask_b32_e64 v112, v107, v224, s[62:63]
	v_cndmask_b32_e64 v114, v108, v224, s[64:65]
	ds_read_b32 v80, v68 offset:32
	ds_read_b32 v81, v68 offset:36
	ds_read_b32 v82, v68 offset:40
	ds_read_b32 v83, v68 offset:44
	ds_read_b32 v105, v68 offset:64
	ds_read_b32 v107, v68 offset:68
	ds_read_b32 v108, v68 offset:72
	ds_read_b32 v109, v68 offset:76
	ds_read_b32 v111, v68 offset:96
	ds_read_b32 v113, v68 offset:100
	ds_read_b32 v115, v68 offset:104
	ds_read_b32 v116, v68 offset:108
	ds_read_b32 v117, v68 offset:128
	ds_read_b32 v118, v68 offset:132
	ds_read_b32 v119, v68 offset:136
	ds_read_b32 v68, v68 offset:140
	s_waitcnt lgkmcnt(14)
	v_fmac_f32_e32 v80, 0x3e000000, v84
	v_cndmask_b32_e64 v79, v224, v78, s[36:37]
	v_cndmask_b32_e64 v78, v224, v124, s[38:39]
	v_cndmask_b32_e64 v124, v80, v224, s[66:67]
	s_waitcnt lgkmcnt(0)
	v_fmac_f32_e32 v68, 0x3e000000, v99
	v_and_b32_e32 v80, 64, v212
	v_cndmask_b32_e64 v173, v224, v68, s[12:13]
	v_xor_b32_e32 v68, 32, v212
	v_add_u32_e32 v80, 64, v80
	v_fmac_f32_e32 v69, 0x3e000000, v100
	v_cmp_lt_i32_e32 vcc, v68, v80
	v_cndmask_b32_e64 v123, v69, v224, s[16:17]
	v_fmac_f32_e32 v71, 0x3e000000, v102
	v_cndmask_b32_e32 v68, v212, v68, vcc
	v_cndmask_b32_e64 v121, v71, v224, s[20:21]
	v_fmac_f32_e32 v73, 0x3e000000, v104
	v_lshlrev_b32_e32 v178, 2, v68
	v_max_f32_e32 v68, 0xf149f2ca, v123
	v_cndmask_b32_e64 v104, v73, v224, s[24:25]
	v_max3_f32 v68, v68, v122, v121
	v_cndmask_b32_e64 v102, v75, v224, s[28:29]
	v_max3_f32 v68, v68, v120, v104
	v_cndmask_b32_e64 v100, v224, v77, s[34:35]
	v_max3_f32 v68, v68, v103, v102
	v_max3_f32 v68, v68, v101, v100
	v_cndmask_b32_e64 v77, v224, v125, s[40:41]
	v_cndmask_b32_e64 v75, v224, v126, s[42:43]
	v_max3_f32 v68, v68, v79, v78
	v_cndmask_b32_e64 v73, v224, v127, s[44:45]
	v_cndmask_b32_e64 v71, v224, v128, s[46:47]
	v_max3_f32 v68, v68, v77, v75
	v_cndmask_b32_e64 v69, v224, v129, s[48:49]
	v_max3_f32 v68, v68, v73, v71
	v_max3_f32 v68, v68, v69, v76
	v_max3_f32 v68, v68, v74, v72
	v_max3_f32 v68, v68, v70, s1
	ds_bpermute_b32 v80, v178, v68
	v_fmac_f32_e32 v111, 0x3e000000, v92
	v_cndmask_b32_e64 v164, v224, v111, s[82:83]
	v_fmac_f32_e32 v113, 0x3e000000, v93
	v_cndmask_b32_e64 v165, v224, v113, s[84:85]
	s_waitcnt lgkmcnt(0)
; DI void osm_update(f32x16 (&acc)[2][2], f32x16 (&o)[2][2], float (&m)[2], float (&l)[2]) {
;     ...
;         const float mn = fmaxf(m[nt], mx), sc = __expf(m[nt] - mn); float sm = 0.f;
; #pragma unroll
;         for (int mt = 0; mt < 2; ++mt)
; #pragma unroll
;             for (int g = 0; g < 16; ++g) { const float pz = __expf(acc[mt][nt][g] - mn); acc[mt][nt][g] = pz; sm += pz; }
;         sm += __shfl_xor(sm, 32);
;         l[nt] = l[nt] * sc + sm; m[nt] = mn;
; #pragma unroll
;         for (int g = 0; g < 16; ++g) { o[0][nt][g] *= sc; o[1][nt][g] *= sc; } }
	v_max3_f32 v68, v245, v68, v80
	v_sub_f32_e32 v69, v69, v68
	v_mul_f32_e32 v69, 0x3fb8aa3b, v69
	v_exp_f32_e32 v111, v69
	v_sub_f32_e32 v69, v76, v68
	v_mul_f32_e32 v69, 0x3fb8aa3b, v69
	v_exp_f32_e32 v113, v69
	v_sub_f32_e32 v69, v74, v68
	v_fmac_f32_e32 v115, 0x3e000000, v94
	v_mul_f32_e32 v69, 0x3fb8aa3b, v69
	v_cndmask_b32_e64 v166, v224, v115, s[86:87]
	v_exp_f32_e32 v115, v69
	v_sub_f32_e32 v69, v72, v68
	v_fmac_f32_e32 v117, 0x3e000000, v96
	v_mul_f32_e32 v69, 0x3fb8aa3b, v69
	v_cndmask_b32_e64 v168, v224, v117, s[14:15]
	v_exp_f32_e32 v117, v69
	v_sub_f32_e32 v69, v70, v68
	v_fmac_f32_e32 v82, 0x3e000000, v86
	v_fmac_f32_e32 v119, 0x3e000000, v98
	v_mul_f32_e32 v69, 0x3fb8aa3b, v69
	v_cndmask_b32_e64 v126, v82, v224, s[70:71]
	v_cndmask_b32_e64 v171, v224, v119, s[8:9]
	v_sub_f32_e32 v82, v122, v68
	v_exp_f32_e32 v119, v69
	v_sub_f32_e32 v69, 0xf149f2ca, v68
	v_cndmask_b32_e64 v106, v106, v224, s[60:61]
	v_fmac_f32_e32 v83, 0x3e000000, v87
	v_mul_f32_e32 v82, 0x3fb8aa3b, v82
	v_mul_f32_e32 v69, 0x3fb8aa3b, v69
	v_fmac_f32_e32 v81, 0x3e000000, v85
	v_cndmask_b32_e64 v127, v83, v224, s[72:73]
	v_exp_f32_e32 v83, v82
	v_sub_f32_e32 v82, v121, v68
	v_exp_f32_e32 v121, v69
	v_max3_f32 v69, v110, s1, v106
	v_cndmask_b32_e64 v125, v81, v224, s[68:69]
	v_max3_f32 v69, v69, v112, v114
	v_fmac_f32_e32 v105, 0x3e000000, v88
	v_fmac_f32_e32 v107, 0x3e000000, v89
	v_max3_f32 v69, v69, v124, v125
	v_cndmask_b32_e64 v128, v224, v105, s[74:75]
	v_cndmask_b32_e64 v129, v224, v107, s[76:77]
	v_fmac_f32_e32 v108, 0x3e000000, v90
	v_fmac_f32_e32 v109, 0x3e000000, v91
	v_max3_f32 v69, v69, v126, v127
	v_cndmask_b32_e64 v130, v224, v108, s[78:79]
	v_cndmask_b32_e64 v131, v224, v109, s[80:81]
	v_sub_f32_e32 v80, v245, v68
	v_max3_f32 v69, v69, v128, v129
	v_fmac_f32_e32 v116, 0x3e000000, v95
	v_mul_f32_e32 v80, 0x3fb8aa3b, v80
	v_max3_f32 v69, v69, v130, v131
	v_cndmask_b32_e64 v167, v224, v116, s[88:89]
	v_fmac_f32_e32 v118, 0x3e000000, v97
	v_exp_f32_e32 v70, v80
	v_max3_f32 v69, v69, v164, v165
	v_cndmask_b32_e64 v169, v224, v118, s[10:11]
	v_max3_f32 v69, v69, v166, v167
	v_sub_f32_e32 v71, v71, v68
	v_max3_f32 v69, v69, v168, v169
	v_mul_f32_e32 v71, 0x3fb8aa3b, v71
	v_max3_f32 v69, v69, v171, v173
	v_exp_f32_e32 v109, v71
	v_pk_mul_f32 v[66:67], v[66:67], v[70:71] op_sel_hi:[1,0]
	v_pk_mul_f32 v[64:65], v[64:65], v[70:71] op_sel_hi:[1,0]
	v_pk_mul_f32 v[62:63], v[62:63], v[70:71] op_sel_hi:[1,0]
	v_pk_mul_f32 v[60:61], v[60:61], v[70:71] op_sel_hi:[1,0]
	v_pk_mul_f32 v[58:59], v[58:59], v[70:71] op_sel_hi:[1,0]
	v_pk_mul_f32 v[56:57], v[56:57], v[70:71] op_sel_hi:[1,0]
	v_pk_mul_f32 v[54:55], v[54:55], v[70:71] op_sel_hi:[1,0]
	v_pk_mul_f32 v[52:53], v[52:53], v[70:71] op_sel_hi:[1,0]
	v_pk_mul_f32 v[34:35], v[34:35], v[70:71] op_sel_hi:[1,0]
	v_pk_mul_f32 v[32:33], v[32:33], v[70:71] op_sel_hi:[1,0]
	v_pk_mul_f32 v[30:31], v[30:31], v[70:71] op_sel_hi:[1,0]
	v_pk_mul_f32 v[28:29], v[28:29], v[70:71] op_sel_hi:[1,0]
	v_pk_mul_f32 v[26:27], v[26:27], v[70:71] op_sel_hi:[1,0]
	v_pk_mul_f32 v[24:25], v[24:25], v[70:71] op_sel_hi:[1,0]
	v_pk_mul_f32 v[22:23], v[22:23], v[70:71] op_sel_hi:[1,0]
	v_pk_mul_f32 v[20:21], v[20:21], v[70:71] op_sel_hi:[1,0]
	ds_bpermute_b32 v71, v178, v69
	v_mul_f32_e32 v82, 0x3fb8aa3b, v82
	v_exp_f32_e32 v85, v82
	v_sub_f32_e32 v82, v120, v68
	v_mul_f32_e32 v82, 0x3fb8aa3b, v82
	s_waitcnt lgkmcnt(0)
	v_max3_f32 v69, v203, v69, v71
	v_sub_f32_e32 v74, v110, v69
	v_mul_f32_e32 v74, 0x3fb8aa3b, v74
	v_exp_f32_e32 v87, v82
	v_sub_f32_e32 v82, v104, v68
	v_exp_f32_e32 v104, v74
	v_sub_f32_e32 v74, v106, v69
	v_mul_f32_e32 v74, 0x3fb8aa3b, v74
	v_mul_f32_e32 v82, 0x3fb8aa3b, v82
	v_exp_f32_e32 v106, v74
	v_sub_f32_e32 v74, v112, v69
	v_exp_f32_e32 v89, v82
	v_sub_f32_e32 v82, v103, v68
	v_mul_f32_e32 v74, 0x3fb8aa3b, v74
	v_mul_f32_e32 v82, 0x3fb8aa3b, v82
	v_exp_f32_e32 v108, v74
	v_sub_f32_e32 v74, v114, v69
	v_sub_f32_e32 v81, v123, v68
	v_exp_f32_e32 v91, v82
	v_sub_f32_e32 v82, v102, v68
	v_sub_f32_e32 v72, 0xf149f2ca, v69
	v_mul_f32_e32 v74, 0x3fb8aa3b, v74
	v_mul_f32_e32 v81, 0x3fb8aa3b, v81
	v_mul_f32_e32 v82, 0x3fb8aa3b, v82
	v_mul_f32_e32 v72, 0x3fb8aa3b, v72
	v_exp_f32_e32 v110, v74
	v_sub_f32_e32 v74, v124, v69
	v_exp_f32_e32 v81, v81
	v_exp_f32_e32 v93, v82
	v_sub_f32_e32 v82, v101, v68
	v_exp_f32_e32 v80, v72
	v_mul_f32_e32 v74, 0x3fb8aa3b, v74
	v_mul_f32_e32 v82, 0x3fb8aa3b, v82
	v_exp_f32_e32 v112, v74
	v_sub_f32_e32 v74, v125, v69
	v_exp_f32_e32 v95, v82
	v_sub_f32_e32 v82, v100, v68
	v_sub_f32_e32 v73, v73, v68
	v_mul_f32_e32 v74, 0x3fb8aa3b, v74
	v_mul_f32_e32 v82, 0x3fb8aa3b, v82
	v_mul_f32_e32 v73, 0x3fb8aa3b, v73
	v_exp_f32_e32 v114, v74
	v_sub_f32_e32 v74, v126, v69
	v_exp_f32_e32 v97, v82
	v_exp_f32_e32 v107, v73
	v_pk_add_f32 v[72:73], v[80:81], 0 op_sel_hi:[1,0]
	v_mov_b32_e32 v82, v80
	v_mul_f32_e32 v74, 0x3fb8aa3b, v74
	v_pk_add_f32 v[72:73], v[82:83], v[72:73]
	v_mov_b32_e32 v84, v80
	v_exp_f32_e32 v116, v74
	v_sub_f32_e32 v74, v127, v69
	v_pk_add_f32 v[72:73], v[84:85], v[72:73]
	v_mov_b32_e32 v86, v80
	v_mul_f32_e32 v74, 0x3fb8aa3b, v74
	v_sub_f32_e32 v79, v79, v68
	v_pk_add_f32 v[72:73], v[86:87], v[72:73]
	v_mov_b32_e32 v88, v80
	v_exp_f32_e32 v118, v74
	v_sub_f32_e32 v74, v128, v69
	v_mul_f32_e32 v79, 0x3fb8aa3b, v79
	v_sub_f32_e32 v78, v78, v68
	v_pk_add_f32 v[72:73], v[88:89], v[72:73]
	v_mov_b32_e32 v90, v80
	v_mul_f32_e32 v74, 0x3fb8aa3b, v74
	v_exp_f32_e32 v99, v79
	v_mul_f32_e32 v78, 0x3fb8aa3b, v78
	v_sub_f32_e32 v77, v77, v68
	v_pk_add_f32 v[72:73], v[90:91], v[72:73]
	v_mov_b32_e32 v92, v80
	v_exp_f32_e32 v120, v74
	v_sub_f32_e32 v74, v129, v69
	v_exp_f32_e32 v101, v78
; #define LAS __attribute__((address_space(3)))
; #define MFMA32(a, b, c) __builtin_amdgcn_mfma_f32_32x32x16_bf16((a), (b), (c), 0, 0, 0)
; DI int tsw(int row) { return ((row >> 4) & 3) << 3; }
; DI void pv_accum(const f32x16 (&acc)[2][2], f32x16 (&o)[2][2], const LAS bf16_t* Vt, int lane) {
;     const int r = lane & 31, hh = lane >> 5;
; #pragma unroll
;     for (int mt = 0; mt < 2; ++mt) {
;         {   const bf16x8 p0 = pack8<0>(acc[mt][0]), p1 = pack8<0>(acc[mt][1]);
; #pragma unroll
;             for (int mo = 0; mo < 2; ++mo) { const LAS bf16_t* s = Vt + (32 * mo + r) * TLD; const int c0 = (32 * mt + 4 * hh) ^ tsw(32 * mo + r);
;                 const u32x2 lo = *(const LAS u32x2*)(s + c0), hi = *(const LAS u32x2*)(s + (c0 ^ 8)); u32x4 w; w.x = lo.x; w.y = lo.y; w.z = hi.x; w.w = hi.y; const bf16x8 vf = __builtin_bit_cast(bf16x8, w);
;                 o[mo][0] = MFMA32(vf, p0, o[mo][0]); o[mo][1] = MFMA32(vf, p1, o[mo][1]); } }
;         {   const bf16x8 p0 = pack8<1>(acc[mt][0]), p1 = pack8<1>(acc[mt][1]);
; #pragma unroll
;             for (int mo = 0; mo < 2; ++mo) { const LAS bf16_t* s = Vt + (32 * mo + r) * TLD; const int c0 = (32 * mt + 16 + 4 * hh) ^ tsw(32 * mo + r);
;                 const u32x2 lo = *(const LAS u32x2*)(s + c0), hi = *(const LAS u32x2*)(s + (c0 ^ 8)); u32x4 w; w.x = lo.x; w.y = lo.y; w.z = hi.x; w.w = hi.y; const bf16x8 vf = __builtin_bit_cast(bf16x8, w);
;                 o[mo][0] = MFMA32(vf, p0, o[mo][0]); o[mo][1] = MFMA32(vf, p1, o[mo][1]); } }
;     }
; }
; DI void osm_update(f32x16 (&acc)[2][2], f32x16 (&o)[2][2], float (&m)[2], float (&l)[2]) {
;     ...
;             for (int g = 0; g < 16; ++g) { const float pz = __expf(acc[mt][nt][g] - mn); acc[mt][nt][g] = pz; sm += pz; }
;         sm += __shfl_xor(sm, 32);
;         l[nt] = l[nt] * sc + sm; m[nt] = mn;
; #pragma unroll
;         for (int g = 0; g < 16; ++g) { o[0][nt][g] *= sc; o[1][nt][g] *= sc; } }
	v_mul_f32_e32 v77, 0x3fb8aa3b, v77
	v_sub_f32_e32 v75, v75, v68
	v_pk_add_f32 v[72:73], v[92:93], v[72:73]
	v_mov_b32_e32 v94, v80
	v_mul_f32_e32 v74, 0x3fb8aa3b, v74
	v_exp_f32_e32 v103, v77
	v_mul_f32_e32 v75, 0x3fb8aa3b, v75
	v_pk_add_f32 v[72:73], v[94:95], v[72:73]
	v_mov_b32_e32 v96, v80
	v_exp_f32_e32 v122, v74
	v_sub_f32_e32 v74, v130, v69
	v_exp_f32_e32 v105, v75
	v_pk_add_f32 v[72:73], v[96:97], v[72:73]
	v_mov_b32_e32 v98, v80
	v_mul_f32_e32 v74, 0x3fb8aa3b, v74
	v_pk_add_f32 v[72:73], v[98:99], v[72:73]
	v_mov_b32_e32 v100, v80
	v_exp_f32_e32 v124, v74
	v_sub_f32_e32 v74, v131, v69
	v_pk_add_f32 v[72:73], v[100:101], v[72:73]
	v_mov_b32_e32 v102, v80
	v_mul_f32_e32 v74, 0x3fb8aa3b, v74
	v_pk_add_f32 v[72:73], v[102:103], v[72:73]
	v_exp_f32_e32 v126, v74
	v_sub_f32_e32 v74, v164, v69
	v_pk_add_f32 v[72:73], v[104:105], v[72:73]
	v_mul_f32_e32 v74, 0x3fb8aa3b, v74
	v_pk_add_f32 v[72:73], v[106:107], v[72:73]
	v_exp_f32_e32 v128, v74
	v_sub_f32_e32 v74, v165, v69
	v_pk_add_f32 v[72:73], v[108:109], v[72:73]
	v_mul_f32_e32 v74, 0x3fb8aa3b, v74
	v_pk_add_f32 v[72:73], v[110:111], v[72:73]
	v_exp_f32_e32 v130, v74
	v_sub_f32_e32 v74, v166, v69
	v_pk_add_f32 v[72:73], v[112:113], v[72:73]
	v_mul_f32_e32 v74, 0x3fb8aa3b, v74
	v_pk_add_f32 v[72:73], v[114:115], v[72:73]
	v_exp_f32_e32 v164, v74
	v_sub_f32_e32 v74, v167, v69
	v_pk_add_f32 v[72:73], v[116:117], v[72:73]
	v_mul_f32_e32 v74, 0x3fb8aa3b, v74
	v_pk_add_f32 v[72:73], v[118:119], v[72:73]
	v_exp_f32_e32 v166, v74
	v_sub_f32_e32 v74, v168, v69
	v_pk_add_f32 v[72:73], v[120:121], v[72:73]
	v_mov_b32_e32 v123, v121
	v_mul_f32_e32 v74, 0x3fb8aa3b, v74
	v_pk_add_f32 v[72:73], v[122:123], v[72:73]
	v_mov_b32_e32 v125, v121
	v_exp_f32_e32 v168, v74
	v_sub_f32_e32 v74, v169, v69
	v_pk_add_f32 v[72:73], v[124:125], v[72:73]
	v_mul_f32_e32 v74, 0x3fb8aa3b, v74
	v_mov_b32_e32 v127, v121
	v_exp_f32_e32 v170, v74
	v_sub_f32_e32 v74, v171, v69
	v_pk_add_f32 v[72:73], v[126:127], v[72:73]
	v_mov_b32_e32 v129, v121
	v_mul_f32_e32 v74, 0x3fb8aa3b, v74
	v_pk_add_f32 v[72:73], v[128:129], v[72:73]
	v_mov_b32_e32 v131, v121
	v_exp_f32_e32 v172, v74
	v_sub_f32_e32 v74, v173, v69
	v_pk_add_f32 v[72:73], v[130:131], v[72:73]
	v_mov_b32_e32 v165, v121
	v_mul_f32_e32 v74, 0x3fb8aa3b, v74
	v_pk_add_f32 v[72:73], v[164:165], v[72:73]
	v_mov_b32_e32 v167, v121
	v_exp_f32_e32 v174, v74
	v_pk_add_f32 v[72:73], v[166:167], v[72:73]
	v_mov_b32_e32 v169, v121
	v_pk_add_f32 v[72:73], v[168:169], v[72:73]
	v_mov_b32_e32 v171, v121
	v_pk_add_f32 v[72:73], v[170:171], v[72:73]
	v_mov_b32_e32 v173, v121
	v_pk_add_f32 v[72:73], v[172:173], v[72:73]
	v_mov_b32_e32 v175, v121
	v_pk_add_f32 v[72:73], v[174:175], v[72:73]
	v_sub_f32_e32 v71, v203, v69
	ds_bpermute_b32 v77, v178, v73
	ds_bpermute_b32 v76, v178, v72
	v_mul_f32_e32 v71, 0x3fb8aa3b, v71
	v_exp_f32_e32 v74, v71
	v_mov_b32_e32 v75, v70
	v_cvt_pk_bf16_f32 v70, v81, v83
	s_waitcnt lgkmcnt(0)
	v_pk_add_f32 v[72:73], v[72:73], v[76:77]
	v_pk_mul_f32 v[50:51], v[50:51], v[74:75] op_sel_hi:[1,0]
	v_pk_fma_f32 v[206:207], v[206:207], v[74:75], v[72:73]
	v_pk_mul_f32 v[48:49], v[48:49], v[74:75] op_sel_hi:[1,0]
	v_pk_mul_f32 v[46:47], v[46:47], v[74:75] op_sel_hi:[1,0]
	v_pk_mul_f32 v[44:45], v[44:45], v[74:75] op_sel_hi:[1,0]
	v_pk_mul_f32 v[42:43], v[42:43], v[74:75] op_sel_hi:[1,0]
	v_pk_mul_f32 v[40:41], v[40:41], v[74:75] op_sel_hi:[1,0]
	v_pk_mul_f32 v[38:39], v[38:39], v[74:75] op_sel_hi:[1,0]
	v_pk_mul_f32 v[36:37], v[36:37], v[74:75] op_sel_hi:[1,0]
	v_pk_mul_f32 v[18:19], v[18:19], v[74:75] op_sel_hi:[1,0]
	v_pk_mul_f32 v[16:17], v[16:17], v[74:75] op_sel_hi:[1,0]
	v_pk_mul_f32 v[14:15], v[14:15], v[74:75] op_sel_hi:[1,0]
	v_pk_mul_f32 v[12:13], v[12:13], v[74:75] op_sel_hi:[1,0]
	v_pk_mul_f32 v[10:11], v[10:11], v[74:75] op_sel_hi:[1,0]
	v_pk_mul_f32 v[8:9], v[8:9], v[74:75] op_sel_hi:[1,0]
	v_pk_mul_f32 v[6:7], v[6:7], v[74:75] op_sel_hi:[1,0]
	v_pk_mul_f32 v[4:5], v[4:5], v[74:75] op_sel_hi:[1,0]
	v_cvt_pk_bf16_f32 v71, v85, v87
	v_cvt_pk_bf16_f32 v74, v80, v80
	ds_read2_b64 v[78:81], v228 offset1:4
	ds_read_b64 v[84:85], v229
	v_cvt_pk_bf16_f32 v72, v89, v91
	v_cvt_pk_bf16_f32 v73, v93, v95
	v_mov_b32_e32 v75, v74
	s_waitcnt lgkmcnt(1)
	v_mov_b32_e32 v82, v78
	v_mov_b32_e32 v83, v79
	v_mov_b32_e32 v76, v74
	v_mov_b32_e32 v77, v74
	s_waitcnt lgkmcnt(0)
	v_mfma_f32_32x32x16_bf16 v[52:67], v[82:85], v[70:73], v[52:67]
	s_addk_i32 s4, 0x80
	s_cmpk_lg_i32 s4, 0x400
	v_mov_b32_e32 v203, v69
	v_mov_b32_e32 v245, v68
	v_mfma_f32_32x32x16_bf16 v[36:51], v[82:85], v[74:77], v[36:51]
	ds_read2_b64 v[82:85], v230 offset1:8
	ds_read_b64 v[88:89], v231
	s_waitcnt lgkmcnt(1)
	v_mov_b32_e32 v86, v82
	v_mov_b32_e32 v87, v83
	s_waitcnt lgkmcnt(0)
	s_nop 0
	v_mfma_f32_32x32x16_bf16 v[20:35], v[86:89], v[70:73], v[20:35]
	v_cvt_pk_bf16_f32 v70, v97, v99
	v_cvt_pk_bf16_f32 v71, v101, v103
	v_cvt_pk_bf16_f32 v72, v105, v107
	v_cvt_pk_bf16_f32 v73, v109, v111
	v_mfma_f32_32x32x16_bf16 v[4:19], v[86:89], v[74:77], v[4:19]
	ds_read2_b64 v[86:89], v228 offset0:8 offset1:12
	ds_read_b64 v[82:83], v232
	v_cvt_pk_bf16_f32 v76, v104, v106
	v_cvt_pk_bf16_f32 v77, v108, v110
	s_waitcnt lgkmcnt(0)
	v_mfma_f32_32x32x16_bf16 v[52:67], v[80:83], v[70:73], v[52:67]
	v_mfma_f32_32x32x16_bf16 v[36:51], v[80:83], v[74:77], v[36:51]
	ds_read_b64 v[78:79], v233
	ds_read_b64 v[80:81], v234
	s_waitcnt lgkmcnt(0)
	v_mfma_f32_32x32x16_bf16 v[20:35], v[78:81], v[70:73], v[20:35]
	v_cvt_pk_bf16_f32 v72, v121, v121
	v_cvt_pk_bf16_f32 v70, v113, v115
	v_cvt_pk_bf16_f32 v71, v117, v119
	v_mov_b32_e32 v73, v72
	v_mfma_f32_32x32x16_bf16 v[4:19], v[78:81], v[74:77], v[4:19]
	ds_read_b64 v[80:81], v235
	v_mov_b32_e32 v78, v86
	v_mov_b32_e32 v79, v87
	v_cvt_pk_bf16_f32 v74, v112, v114
	v_cvt_pk_bf16_f32 v75, v116, v118
	v_cvt_pk_bf16_f32 v76, v120, v122
	v_cvt_pk_bf16_f32 v77, v124, v126
	s_waitcnt lgkmcnt(0)
	v_mfma_f32_32x32x16_bf16 v[52:67], v[78:81], v[70:73], v[52:67]
	v_mfma_f32_32x32x16_bf16 v[36:51], v[78:81], v[74:77], v[36:51]
	ds_read_b64 v[80:81], v236
	v_mov_b32_e32 v78, v84
	v_mov_b32_e32 v79, v85
	s_waitcnt lgkmcnt(0)
	s_nop 0
	v_mfma_f32_32x32x16_bf16 v[20:35], v[78:81], v[70:73], v[20:35]
	v_mov_b32_e32 v70, v72
	v_mov_b32_e32 v71, v72
	v_mfma_f32_32x32x16_bf16 v[4:19], v[78:81], v[74:77], v[4:19]
	ds_read_b64 v[80:81], v237
	v_mov_b32_e32 v78, v88
	v_mov_b32_e32 v79, v89
	v_cvt_pk_bf16_f32 v74, v128, v130
	v_cvt_pk_bf16_f32 v75, v164, v166
	v_cvt_pk_bf16_f32 v76, v168, v170
	v_cvt_pk_bf16_f32 v77, v172, v174
	s_waitcnt lgkmcnt(0)
	v_mfma_f32_32x32x16_bf16 v[52:67], v[78:81], v[70:73], v[52:67]
	v_mfma_f32_32x32x16_bf16 v[36:51], v[78:81], v[74:77], v[36:51]
	ds_read_b64 v[78:79], v238
	ds_read_b64 v[80:81], v239
	s_waitcnt lgkmcnt(0)
	v_mfma_f32_32x32x16_bf16 v[20:35], v[78:81], v[70:73], v[20:35]
	v_mfma_f32_32x32x16_bf16 v[4:19], v[78:81], v[74:77], v[4:19]
	s_cbranch_scc1 .LBB0_661
; #define LAS __attribute__((address_space(3)))
; DI unsigned pk2(float lo, float hi) { f32x2 v = {lo, hi}; bf16x2v b = __builtin_convertvector(v, bf16x2v); return __builtin_bit_cast(unsigned, b); }
; DI float frcp(float x) { return __builtin_amdgcn_rcpf(x); }
; template <class F> DI void store_o_rows(LAS bf16_t* T, const f32x16 (&o)[2][2], const float (&scale)[2], int lane, F rowp) {
;     const int r = lane & 31, hh = lane >> 5;
; #pragma unroll
;     for (int mo = 0; mo < 2; ++mo)
; #pragma unroll
;         for (int nt = 0; nt < 2; ++nt)
; #pragma unroll
;             for (int g = 0; g < 4; ++g) { u32x2 w; w.x = pk2(o[mo][nt][4 * g] * scale[nt], o[mo][nt][4 * g + 1] * scale[nt]); w.y = pk2(o[mo][nt][4 * g + 2] * scale[nt], o[mo][nt][4 * g + 3] * scale[nt]);
;                 *(LAS u32x2*)(T + (32 * nt + r) * TLD + 32 * mo + 8 * g + 4 * hh) = w; }
;     asm volatile("s_waitcnt lgkmcnt(0)" ::: "memory");
; #pragma unroll
;     for (int it = 0; it < 8; ++it) { const int id = it * 64 + lane, q = id >> 3, part = id & 7; *(u32x4*)(rowp(q) + 8 * part) = *(const LAS u32x4*)(T + q * TLD + 8 * part); }
;     asm volatile("s_waitcnt lgkmcnt(0)" ::: "memory");
; }
; DI void na_wave_unit(KArgs args, LAS unsigned char* L, const Ctx& c, int u, int lane, int wave) {
;     ...
;     asm volatile("s_waitcnt lgkmcnt(0)" ::: "memory");
;     const float sc[2] = {frcp(ls[0]), frcp(ls[1])};
;     store_o_rows(Vt, o, sc, lane, [&](int q) { return BIGP(bf16_t, B_ONA) + (tq0 + q) * 768 + 64 * head; });
	v_rcp_f32_e32 v68, v207
	v_rcp_f32_e32 v70, v206
	s_waitcnt lgkmcnt(0)
	v_readlane_b32 s0, v254, 42
	s_nop 1
	v_pk_mul_f32 v[52:53], v[52:53], v[68:69] op_sel_hi:[1,0]
	v_pk_mul_f32 v[54:55], v[54:55], v[68:69] op_sel_hi:[1,0]
	v_cvt_pk_bf16_f32 v52, v52, v53
	v_cvt_pk_bf16_f32 v53, v54, v55
	v_pk_mul_f32 v[54:55], v[56:57], v[68:69] op_sel_hi:[1,0]
	v_pk_mul_f32 v[56:57], v[58:59], v[68:69] op_sel_hi:[1,0]
	v_cvt_pk_bf16_f32 v54, v54, v55
	v_cvt_pk_bf16_f32 v55, v56, v57
	ds_write2_b64 v242, v[52:53], v[54:55] offset1:2
	v_pk_mul_f32 v[52:53], v[60:61], v[68:69] op_sel_hi:[1,0]
	v_pk_mul_f32 v[54:55], v[62:63], v[68:69] op_sel_hi:[1,0]
	v_pk_mul_f32 v[36:37], v[36:37], v[70:71] op_sel_hi:[1,0]
	v_pk_mul_f32 v[38:39], v[38:39], v[70:71] op_sel_hi:[1,0]
	v_cvt_pk_bf16_f32 v52, v52, v53
	v_cvt_pk_bf16_f32 v53, v54, v55
	v_pk_mul_f32 v[54:55], v[64:65], v[68:69] op_sel_hi:[1,0]
	v_pk_mul_f32 v[56:57], v[66:67], v[68:69] op_sel_hi:[1,0]
	v_cvt_pk_bf16_f32 v36, v36, v37
	v_cvt_pk_bf16_f32 v37, v38, v39
	v_pk_mul_f32 v[38:39], v[40:41], v[70:71] op_sel_hi:[1,0]
	v_pk_mul_f32 v[40:41], v[42:43], v[70:71] op_sel_hi:[1,0]
	v_cvt_pk_bf16_f32 v54, v54, v55
	v_cvt_pk_bf16_f32 v55, v56, v57
	v_cvt_pk_bf16_f32 v38, v38, v39
	v_cvt_pk_bf16_f32 v39, v40, v41
	ds_write2_b64 v242, v[52:53], v[54:55] offset0:4 offset1:6
	ds_write2_b64 v243, v[36:37], v[38:39] offset1:2
	v_pk_mul_f32 v[36:37], v[44:45], v[70:71] op_sel_hi:[1,0]
	v_pk_mul_f32 v[38:39], v[46:47], v[70:71] op_sel_hi:[1,0]
	v_pk_mul_f32 v[20:21], v[20:21], v[68:69] op_sel_hi:[1,0]
	v_pk_mul_f32 v[22:23], v[22:23], v[68:69] op_sel_hi:[1,0]
	v_cvt_pk_bf16_f32 v36, v36, v37
	v_cvt_pk_bf16_f32 v37, v38, v39
	v_pk_mul_f32 v[38:39], v[48:49], v[70:71] op_sel_hi:[1,0]
	v_pk_mul_f32 v[40:41], v[50:51], v[70:71] op_sel_hi:[1,0]
	v_cvt_pk_bf16_f32 v20, v20, v21
	v_cvt_pk_bf16_f32 v21, v22, v23
	v_pk_mul_f32 v[22:23], v[24:25], v[68:69] op_sel_hi:[1,0]
	v_pk_mul_f32 v[24:25], v[26:27], v[68:69] op_sel_hi:[1,0]
	v_cvt_pk_bf16_f32 v38, v38, v39
	v_cvt_pk_bf16_f32 v39, v40, v41
	v_cvt_pk_bf16_f32 v22, v22, v23
	v_cvt_pk_bf16_f32 v23, v24, v25
	ds_write2_b64 v243, v[36:37], v[38:39] offset0:4 offset1:6
	ds_write2_b64 v242, v[20:21], v[22:23] offset0:8 offset1:10
	v_pk_mul_f32 v[20:21], v[28:29], v[68:69] op_sel_hi:[1,0]
	v_pk_mul_f32 v[22:23], v[30:31], v[68:69] op_sel_hi:[1,0]
	v_pk_mul_f32 v[4:5], v[4:5], v[70:71] op_sel_hi:[1,0]
	v_pk_mul_f32 v[6:7], v[6:7], v[70:71] op_sel_hi:[1,0]
	v_cvt_pk_bf16_f32 v20, v20, v21
	v_cvt_pk_bf16_f32 v21, v22, v23
	v_pk_mul_f32 v[22:23], v[32:33], v[68:69] op_sel_hi:[1,0]
	v_pk_mul_f32 v[24:25], v[34:35], v[68:69] op_sel_hi:[1,0]
	v_cvt_pk_bf16_f32 v4, v4, v5
	v_cvt_pk_bf16_f32 v5, v6, v7
	v_pk_mul_f32 v[6:7], v[8:9], v[70:71] op_sel_hi:[1,0]
	v_pk_mul_f32 v[8:9], v[10:11], v[70:71] op_sel_hi:[1,0]
	v_cvt_pk_bf16_f32 v22, v22, v23
	v_cvt_pk_bf16_f32 v23, v24, v25
	v_cvt_pk_bf16_f32 v6, v6, v7
	v_cvt_pk_bf16_f32 v7, v8, v9
	ds_write2_b64 v242, v[20:21], v[22:23] offset0:12 offset1:14
	ds_write2_b64 v243, v[4:5], v[6:7] offset0:8 offset1:10
	v_pk_mul_f32 v[4:5], v[12:13], v[70:71] op_sel_hi:[1,0]
	v_pk_mul_f32 v[6:7], v[14:15], v[70:71] op_sel_hi:[1,0]
	v_cvt_pk_bf16_f32 v4, v4, v5
	v_cvt_pk_bf16_f32 v5, v6, v7
	v_pk_mul_f32 v[6:7], v[16:17], v[70:71] op_sel_hi:[1,0]
	v_pk_mul_f32 v[8:9], v[18:19], v[70:71] op_sel_hi:[1,0]
	v_cvt_pk_bf16_f32 v6, v6, v7
	v_cvt_pk_bf16_f32 v7, v8, v9
	ds_write2_b64 v243, v[4:5], v[6:7] offset0:12 offset1:14
	s_waitcnt lgkmcnt(0)
	v_readlane_b32 s4, v254, 56
	v_readlane_b32 s1, v254, 43
	ds_read_b128 v[4:7], v244
	v_or_b32_e32 v8, s4, v182
	v_mov_b64_e32 v[12:13], s[0:1]
	s_movk_i32 s0, 0x600
	v_mad_u64_u32 v[8:9], s[2:3], v8, s0, v[12:13]
	v_readlane_b32 s1, v254, 58
	v_mov_b32_e32 v203, v3
	s_movk_i32 s33, 0x600
	v_mad_u32_u24 v9, s1, v225, v9
	v_lshl_add_u64 v[8:9], v[8:9], 0, s[92:93]
	v_lshl_add_u64 v[14:15], v[8:9], 0, v[202:203]
	ds_read_b128 v[8:11], v244 offset:1152
	s_waitcnt lgkmcnt(1)
	global_store_dwordx4 v[14:15], v[4:7], off
	s_nop 1
	v_or_b32_e32 v4, s4, v184
	v_mad_u64_u32 v[4:5], s[2:3], v4, s0, v[12:13]
	v_mad_u32_u24 v5, s1, v225, v5
	v_lshl_add_u64 v[4:5], v[4:5], 0, s[92:93]
	v_lshl_add_u64 v[4:5], v[4:5], 0, v[202:203]
	s_waitcnt lgkmcnt(0)
	global_store_dwordx4 v[4:5], v[8:11], off
	ds_read_b128 v[4:7], v244 offset:2304
	s_nop 0
	v_or_b32_e32 v8, s4, v186
	v_mad_u64_u32 v[8:9], s[2:3], v8, s0, v[12:13]
	v_mad_u32_u24 v9, s1, v225, v9
	v_lshl_add_u64 v[8:9], v[8:9], 0, s[92:93]
	v_lshl_add_u64 v[14:15], v[8:9], 0, v[202:203]
	ds_read_b128 v[8:11], v244 offset:3456
	s_waitcnt lgkmcnt(1)
	global_store_dwordx4 v[14:15], v[4:7], off
	s_nop 1
	v_or_b32_e32 v4, s4, v188
	v_mad_u64_u32 v[4:5], s[2:3], v4, s0, v[12:13]
	v_mad_u32_u24 v5, s1, v225, v5
	v_lshl_add_u64 v[4:5], v[4:5], 0, s[92:93]
	v_lshl_add_u64 v[4:5], v[4:5], 0, v[202:203]
	s_waitcnt lgkmcnt(0)
	global_store_dwordx4 v[4:5], v[8:11], off
	ds_read_b128 v[4:7], v244 offset:4608
	s_nop 0
	v_or_b32_e32 v8, s4, v190
	v_mad_u64_u32 v[8:9], s[2:3], v8, s0, v[12:13]
	v_mad_u32_u24 v9, s1, v225, v9
	v_lshl_add_u64 v[8:9], v[8:9], 0, s[92:93]
	v_lshl_add_u64 v[14:15], v[8:9], 0, v[202:203]
	ds_read_b128 v[8:11], v244 offset:5760
	s_waitcnt lgkmcnt(1)
	global_store_dwordx4 v[14:15], v[4:7], off
	s_nop 1
	v_or_b32_e32 v4, s4, v192
	v_mad_u64_u32 v[4:5], s[2:3], v4, s0, v[12:13]
	v_mad_u32_u24 v5, s1, v225, v5
	v_lshl_add_u64 v[4:5], v[4:5], 0, s[92:93]
	v_lshl_add_u64 v[4:5], v[4:5], 0, v[202:203]
	s_waitcnt lgkmcnt(0)
	global_store_dwordx4 v[4:5], v[8:11], off
	ds_read_b128 v[4:7], v244 offset:6912
	s_nop 0
	v_or_b32_e32 v8, s4, v194
	v_mad_u64_u32 v[8:9], s[2:3], v8, s0, v[12:13]
	v_mad_u32_u24 v9, s1, v225, v9
	v_lshl_add_u64 v[8:9], v[8:9], 0, s[92:93]
	v_lshl_add_u64 v[14:15], v[8:9], 0, v[202:203]
	ds_read_b128 v[8:11], v244 offset:8064
	s_waitcnt lgkmcnt(1)
	global_store_dwordx4 v[14:15], v[4:7], off
	s_nop 1
	v_or_b32_e32 v4, s4, v196
	v_mad_u64_u32 v[4:5], s[2:3], v4, s0, v[12:13]
	v_mad_u32_u24 v5, s1, v225, v5
	v_lshl_add_u64 v[4:5], v[4:5], 0, s[92:93]
	v_lshl_add_u64 v[4:5], v[4:5], 0, v[202:203]
	s_waitcnt lgkmcnt(0)
	global_store_dwordx4 v[4:5], v[8:11], off
	s_waitcnt lgkmcnt(0)
	s_mov_b64 s[0:1], 0
	s_branch .LBB0_652

; #define LAS __attribute__((address_space(3)))
; DI float bflo(unsigned u) { return __uint_as_float(u << 16); }
; DI void rope_load(RopeCS& t, const float* cs, int hh) {
; #pragma unroll
;     for (int ks = 0; ks < 2; ++ks) { const float* cp = cs + 16 * ks + 8 * hh; t.v[ks][0] = *(const f32x4*)cp; t.v[ks][1] = *(const f32x4*)(cp + 4); t.v[ks][2] = *(const f32x4*)(cp + 32); t.v[ks][3] = *(const f32x4*)(cp + 36); }
; }
; DI void rope_frag4(bf16x8 (&f)[4], const RopeCS& t) {
; #pragma unroll
;     for (int ks = 0; ks < 2; ++ks) {
;         const f32x4 c0 = t.v[ks][0], c1 = t.v[ks][1], s0 = t.v[ks][2], s1 = t.v[ks][3];
;         const u32x4 a = __builtin_bit_cast(u32x4, f[ks]), b = __builtin_bit_cast(u32x4, f[ks + 2]); u32x4 ra, rb;
; #pragma unroll
;         for (int j = 0; j < 4; ++j) { const float cl = (j < 2) ? c0[2 * j] : c1[2 * j - 4], ch = (j < 2) ? c0[2 * j + 1] : c1[2 * j - 3];
;             const float sl = (j < 2) ? s0[2 * j] : s1[2 * j - 4], sh = (j < 2) ? s0[2 * j + 1] : s1[2 * j - 3];
;             const float x1l = bflo(a[j]), x1h = bfhi(a[j]), x2l = bflo(b[j]), x2h = bfhi(b[j]);
;             ra[j] = pk2(x1l * cl - x2l * sl, x1h * ch - x2h * sh); rb[j] = pk2(x1l * sl + x2l * cl, x1h * sh + x2h * ch); }
;         f[ks] = __builtin_bit_cast(bf16x8, ra); f[ks + 2] = __builtin_bit_cast(bf16x8, rb); }
; DI void dil_wave_unit(KArgs args, LAS unsigned char* L, const Ctx& c, int u, int lane, int wave) {
;     const int hd = u & 1, uu = u >> 1, upg = c.stok >> 6, g = uu / upg, v = uu % upg, ups = c.seqlen >> 6, seq = v / ups, wq = v % ups;
;     const int dsh = 2 * g, dd = 1 << dsh, nb = ups >> dsh, cls = wq / nb, jb = wq % nb, head = 2 * g + hd;
;     const bf16_t* PROJ = BIGP(bf16_t, B_PROJ); const float* CS = WSP(float, WS_CS);
;     const size_t sb = (size_t)seq * c.seqlen;
;     const int rr = lane & 31, hh = lane >> 5;
;     LAS bf16_t* Vt = (LAS bf16_t*)(L + wave * WAREA);
;     bf16x8 qf[2][4];
; #pragma unroll
;     for (int nt = 0; nt < 2; ++nt) { const int pos = cls + dd * (64 * jb + 32 * nt + rr);
; #pragma unroll
;         for (int ks = 0; ks < 4; ++ks) qf[nt][ks] = *(const bf16x8*)(PROJ + (sb + pos) * NPROJ + C_QD + 64 * head + 16 * ks + 8 * hh);
;         RopeCS tq; rope_load(tq, CS + (size_t)pos * 64, hh); __builtin_amdgcn_sched_barrier(0);
;         rope_frag4(qf[nt], tq); }
.Ldil_body:
	s_and_b32 s58, s33, 1
	s_lshr_b32 s33, s33, 1
	v_readlane_b32 s54, v255, 34
	s_lshr_b32 s92, s33, s54
	v_readlane_b32 s54, v255, 35
	s_and_b32 s33, s33, s54
	v_readlane_b32 s57, v254, 32
	v_readlane_b32 s55, v254, 33
	s_lshr_b32 s54, s33, s57
	s_and_b32 s55, s33, s55
	s_lshl_b32 s33, s92, 1
	v_readlane_b32 s56, v254, 36
	s_lshr_b32 s63, s56, s33
	s_sub_i32 s56, s57, s33
	s_lshr_b32 s64, s55, s56
	s_add_i32 s56, s63, -1
	s_and_b32 s65, s55, s56
	s_lshl_b32 s62, s65, 6
	v_writelane_b32 v254, s58, 40
	v_or_b32_e32 v191, s62, v179
	s_mov_b32 s55, s93
	v_readlane_b32 s56, v254, 39
	v_lshlrev_b32_e32 v2, s33, v191
	s_lshl_b64 s[54:55], s[54:55], s56
	v_add_u32_e32 v2, s64, v2
	v_lshl_add_u64 v[6:7], s[54:55], 0, v[2:3]
	v_mov_b64_e32 v[4:5], s[6:7]
	s_or_b32 s58, s33, s58
	v_mad_u64_u32 v[8:9], s[56:57], v6, s90, v[4:5]
	v_mad_u32_u24 v9, v7, s90, v9
	s_lshl_b32 vcc_lo, s58, 7
	s_mov_b32 vcc_hi, s93
	v_lshl_add_u64 v[6:7], v[8:9], 0, vcc
	v_mov_b32_e32 v189, v3
	v_lshlrev_b64 v[22:23], 8, v[2:3]
	v_lshl_add_u64 v[18:19], v[6:7], 0, v[188:189]
	v_lshl_add_u64 v[50:51], v[182:183], 0, v[22:23]
	global_load_dwordx4 v[6:9], v[18:19], off offset:1536
	global_load_dwordx4 v[10:13], v[18:19], off offset:1568
	global_load_dwordx4 v[14:17], v[18:19], off offset:1600
	global_load_dwordx4 v[18:21], v[18:19], off offset:1632
	s_nop 0
	global_load_dwordx4 v[22:25], v[50:51], off offset:16
	global_load_dwordx4 v[26:29], v[50:51], off
	global_load_dwordx4 v[30:33], v[50:51], off offset:144
	global_load_dwordx4 v[34:37], v[50:51], off offset:128
	global_load_dwordx4 v[38:41], v[50:51], off offset:80
	global_load_dwordx4 v[42:45], v[50:51], off offset:64
	global_load_dwordx4 v[46:49], v[50:51], off offset:208
	global_load_dwordx4 v[50:53], v[50:51], off offset:192
	s_waitcnt vmcnt(0)
	v_lshlrev_b32_e32 v54, 16, v6
	v_and_b32_e32 v55, 0xffff0000, v6
	v_lshlrev_b32_e32 v56, 16, v14
	v_and_b32_e32 v57, 0xffff0000, v14
	v_pk_mul_f32 v[58:59], v[34:35], v[56:57]
	v_pk_mul_f32 v[34:35], v[34:35], v[54:55]
	v_pk_fma_f32 v[58:59], v[26:27], v[54:55], v[58:59] neg_lo:[0,0,1] neg_hi:[0,0,1]
	v_pk_fma_f32 v[26:27], v[26:27], v[56:57], v[34:35]
	v_lshlrev_b32_e32 v14, 16, v15
	v_and_b32_e32 v15, 0xffff0000, v15
	v_cvt_pk_bf16_f32 v150, v26, v27
	v_lshlrev_b32_e32 v6, 16, v7
	v_and_b32_e32 v7, 0xffff0000, v7
	v_pk_mul_f32 v[26:27], v[36:37], v[14:15]
	v_or_b32_e32 v2, 32, v191
	v_pk_fma_f32 v[26:27], v[28:29], v[6:7], v[26:27] neg_lo:[0,0,1] neg_hi:[0,0,1]
	v_pk_mul_f32 v[6:7], v[36:37], v[6:7]
	v_cvt_pk_bf16_f32 v147, v26, v27
	v_pk_fma_f32 v[6:7], v[28:29], v[14:15], v[6:7]
	v_lshlrev_b32_e32 v14, 16, v16
	v_and_b32_e32 v15, 0xffff0000, v16
	v_cvt_pk_bf16_f32 v151, v6, v7
	v_lshlrev_b32_e32 v6, 16, v8
	v_and_b32_e32 v7, 0xffff0000, v8
	v_pk_mul_f32 v[26:27], v[30:31], v[14:15]
	v_lshlrev_b32_e32 v8, 16, v17
	v_pk_fma_f32 v[26:27], v[22:23], v[6:7], v[26:27] neg_lo:[0,0,1] neg_hi:[0,0,1]
	v_pk_mul_f32 v[6:7], v[30:31], v[6:7]
	v_lshlrev_b32_e32 v2, s33, v2
	v_pk_fma_f32 v[6:7], v[22:23], v[14:15], v[6:7]
	v_add_u32_e32 v2, s64, v2
	v_cvt_pk_bf16_f32 v152, v6, v7
	v_lshlrev_b32_e32 v6, 16, v9
	v_and_b32_e32 v7, 0xffff0000, v9
	v_and_b32_e32 v9, 0xffff0000, v17
	v_pk_mul_f32 v[14:15], v[32:33], v[8:9]
	v_cvt_pk_bf16_f32 v148, v26, v27
	v_pk_fma_f32 v[14:15], v[24:25], v[6:7], v[14:15] neg_lo:[0,0,1] neg_hi:[0,0,1]
	v_pk_mul_f32 v[6:7], v[32:33], v[6:7]
	v_cvt_pk_bf16_f32 v149, v14, v15
	v_pk_fma_f32 v[6:7], v[24:25], v[8:9], v[6:7]
	v_lshlrev_b32_e32 v8, 16, v10
	v_and_b32_e32 v9, 0xffff0000, v10
	v_cvt_pk_bf16_f32 v153, v6, v7
	v_lshlrev_b32_e32 v6, 16, v18
	v_and_b32_e32 v7, 0xffff0000, v18
	v_pk_mul_f32 v[14:15], v[50:51], v[8:9]
	v_cvt_pk_bf16_f32 v146, v58, v59
	v_pk_fma_f32 v[14:15], v[42:43], v[6:7], v[14:15]
	v_pk_mul_f32 v[6:7], v[50:51], v[6:7]
	v_cvt_pk_bf16_f32 v154, v14, v15
	v_pk_fma_f32 v[6:7], v[42:43], v[8:9], v[6:7] neg_lo:[0,0,1] neg_hi:[0,0,1]
	v_lshlrev_b32_e32 v8, 16, v11
	v_and_b32_e32 v9, 0xffff0000, v11
	v_cvt_pk_bf16_f32 v158, v6, v7
	v_lshlrev_b32_e32 v6, 16, v19
	v_and_b32_e32 v7, 0xffff0000, v19
	v_pk_mul_f32 v[10:11], v[52:53], v[8:9]
	s_nop 0
	v_pk_fma_f32 v[10:11], v[44:45], v[6:7], v[10:11]
	v_pk_mul_f32 v[6:7], v[52:53], v[6:7]
	v_cvt_pk_bf16_f32 v155, v10, v11
	v_pk_fma_f32 v[6:7], v[44:45], v[8:9], v[6:7] neg_lo:[0,0,1] neg_hi:[0,0,1]
	v_lshlrev_b32_e32 v8, 16, v12
	v_and_b32_e32 v9, 0xffff0000, v12
	v_cvt_pk_bf16_f32 v159, v6, v7
	v_lshlrev_b32_e32 v6, 16, v20
	v_and_b32_e32 v7, 0xffff0000, v20
	v_pk_mul_f32 v[10:11], v[46:47], v[8:9]
	s_nop 0
	v_pk_fma_f32 v[10:11], v[38:39], v[6:7], v[10:11]
	v_pk_mul_f32 v[6:7], v[46:47], v[6:7]
	v_cvt_pk_bf16_f32 v156, v10, v11
	v_pk_fma_f32 v[6:7], v[38:39], v[8:9], v[6:7] neg_lo:[0,0,1] neg_hi:[0,0,1]
	v_lshlrev_b32_e32 v8, 16, v21
	v_and_b32_e32 v9, 0xffff0000, v21
	v_cvt_pk_bf16_f32 v160, v6, v7
	v_lshlrev_b32_e32 v6, 16, v13
	v_and_b32_e32 v7, 0xffff0000, v13
	v_pk_mul_f32 v[10:11], v[48:49], v[8:9]
	s_nop 0
	v_pk_fma_f32 v[10:11], v[40:41], v[6:7], v[10:11] neg_lo:[0,0,1] neg_hi:[0,0,1]
	v_pk_mul_f32 v[6:7], v[48:49], v[6:7]
	v_cvt_pk_bf16_f32 v161, v10, v11
	v_pk_fma_f32 v[6:7], v[40:41], v[8:9], v[6:7]
	s_nop 0
	v_cvt_pk_bf16_f32 v157, v6, v7
	v_lshl_add_u64 v[6:7], s[54:55], 0, v[2:3]
	v_mad_u64_u32 v[4:5], s[56:57], v6, s90, v[4:5]
	v_mad_u32_u24 v5, v7, s90, v5
	v_lshl_add_u64 v[4:5], v[4:5], 0, vcc
	v_lshl_add_u64 v[4:5], v[4:5], 0, v[188:189]
	global_load_dwordx4 v[40:43], v[4:5], off offset:1536
	global_load_dwordx4 v[16:19], v[4:5], off offset:1568
	global_load_dwordx4 v[36:39], v[4:5], off offset:1600
	global_load_dwordx4 v[12:15], v[4:5], off offset:1632
	v_lshlrev_b64 v[4:5], 8, v[2:3]
	v_lshl_add_u64 v[24:25], v[182:183], 0, v[4:5]
	global_load_dwordx4 v[28:31], v[24:25], off offset:16
	global_load_dwordx4 v[44:47], v[24:25], off
	global_load_dwordx4 v[32:35], v[24:25], off offset:144
	global_load_dwordx4 v[48:51], v[24:25], off offset:128
	global_load_dwordx4 v[4:7], v[24:25], off offset:80
	global_load_dwordx4 v[20:23], v[24:25], off offset:64
	global_load_dwordx4 v[8:11], v[24:25], off offset:208
	global_load_dwordx4 v[24:27], v[24:25], off offset:192
	s_waitcnt vmcnt(11)
; DI f32x16 zero16() { f32x16 z; for (int i = 0; i < 16; ++i) z[i] = 0.f; return z; }
; DI void dil_wave_unit(KArgs args, LAS unsigned char* L, const Ctx& c, int u, int lane, int wave) {
;     ...
;     for (int nt = 0; nt < 2; ++nt) { const int pos = cls + dd * (64 * jb + 32 * nt + rr);
; #pragma unroll
;         for (int ks = 0; ks < 4; ++ks) qf[nt][ks] = *(const bf16x8*)(PROJ + (sb + pos) * NPROJ + C_QD + 64 * head + 16 * ks + 8 * hh);
;         RopeCS tq; rope_load(tq, CS + (size_t)pos * 64, hh); __builtin_amdgcn_sched_barrier(0);
;         rope_frag4(qf[nt], tq); }
;     f32x16 o[2][2]; o[0][0] = zero16(); o[0][1] = zero16(); o[1][0] = zero16(); o[1][1] = zero16();
;     float m[2] = {-1e30f, -1e30f}, ls[2] = {0.f, 0.f};
	v_lshlrev_b32_e32 v52, 16, v40
	v_and_b32_e32 v53, 0xffff0000, v40
	s_waitcnt vmcnt(9)
	v_lshlrev_b32_e32 v54, 16, v36
	v_and_b32_e32 v55, 0xffff0000, v36
	s_waitcnt vmcnt(4)
	v_pk_mul_f32 v[56:57], v[48:49], v[54:55]
	v_pk_mul_f32 v[48:49], v[48:49], v[52:53]
	v_pk_fma_f32 v[56:57], v[44:45], v[52:53], v[56:57] neg_lo:[0,0,1] neg_hi:[0,0,1]
	v_pk_fma_f32 v[44:45], v[44:45], v[54:55], v[48:49]
	v_lshlrev_b32_e32 v36, 16, v37
	v_and_b32_e32 v37, 0xffff0000, v37
	v_cvt_pk_bf16_f32 v166, v44, v45
	v_lshlrev_b32_e32 v40, 16, v41
	v_and_b32_e32 v41, 0xffff0000, v41
	v_pk_mul_f32 v[44:45], v[50:51], v[36:37]
	s_add_i32 s65, s65, -1
	v_pk_fma_f32 v[44:45], v[46:47], v[40:41], v[44:45] neg_lo:[0,0,1] neg_hi:[0,0,1]
	v_pk_mul_f32 v[40:41], v[50:51], v[40:41]
	v_cvt_pk_bf16_f32 v163, v44, v45
	v_pk_fma_f32 v[36:37], v[46:47], v[36:37], v[40:41]
	v_lshlrev_b32_e32 v40, 16, v38
	v_cvt_pk_bf16_f32 v167, v36, v37
	v_lshlrev_b32_e32 v36, 16, v42
	v_and_b32_e32 v37, 0xffff0000, v42
	v_and_b32_e32 v41, 0xffff0000, v38
	v_pk_mul_f32 v[44:45], v[32:33], v[40:41]
	v_pk_mul_f32 v[32:33], v[32:33], v[36:37]
	v_pk_fma_f32 v[44:45], v[28:29], v[36:37], v[44:45] neg_lo:[0,0,1] neg_hi:[0,0,1]
	v_pk_fma_f32 v[28:29], v[28:29], v[40:41], v[32:33]
	v_lshlrev_b32_e32 v32, 16, v39
	v_and_b32_e32 v33, 0xffff0000, v39
	v_cvt_pk_bf16_f32 v168, v28, v29
	v_lshlrev_b32_e32 v28, 16, v43
	v_and_b32_e32 v29, 0xffff0000, v43
	v_pk_mul_f32 v[36:37], v[34:35], v[32:33]
	v_cvt_pk_bf16_f32 v162, v56, v57
	v_pk_fma_f32 v[36:37], v[30:31], v[28:29], v[36:37] neg_lo:[0,0,1] neg_hi:[0,0,1]
	v_pk_mul_f32 v[28:29], v[34:35], v[28:29]
	v_cvt_pk_bf16_f32 v164, v44, v45
	v_pk_fma_f32 v[28:29], v[30:31], v[32:33], v[28:29]
	v_lshlrev_b32_e32 v30, 16, v16
	v_cvt_pk_bf16_f32 v169, v28, v29
	v_lshlrev_b32_e32 v28, 16, v12
	v_and_b32_e32 v29, 0xffff0000, v12
	v_and_b32_e32 v31, 0xffff0000, v16
	s_waitcnt vmcnt(0)
	v_pk_mul_f32 v[32:33], v[24:25], v[30:31]
	v_pk_mul_f32 v[24:25], v[24:25], v[28:29]
	v_pk_fma_f32 v[32:33], v[20:21], v[28:29], v[32:33]
	v_pk_fma_f32 v[20:21], v[20:21], v[30:31], v[24:25] neg_lo:[0,0,1] neg_hi:[0,0,1]
	v_lshlrev_b32_e32 v16, 16, v17
	v_and_b32_e32 v17, 0xffff0000, v17
	v_cvt_pk_bf16_f32 v174, v20, v21
	v_lshlrev_b32_e32 v12, 16, v13
	v_and_b32_e32 v13, 0xffff0000, v13
	v_pk_mul_f32 v[20:21], v[26:27], v[16:17]
	v_cvt_pk_bf16_f32 v165, v36, v37
	v_pk_fma_f32 v[20:21], v[22:23], v[12:13], v[20:21]
	v_pk_mul_f32 v[12:13], v[26:27], v[12:13]
	v_cvt_pk_bf16_f32 v171, v20, v21
	v_pk_fma_f32 v[12:13], v[22:23], v[16:17], v[12:13] neg_lo:[0,0,1] neg_hi:[0,0,1]
	v_lshlrev_b32_e32 v16, 16, v18
	v_cvt_pk_bf16_f32 v175, v12, v13
	v_lshlrev_b32_e32 v12, 16, v14
	v_and_b32_e32 v13, 0xffff0000, v14
	v_and_b32_e32 v17, 0xffff0000, v18
	v_pk_mul_f32 v[20:21], v[8:9], v[16:17]
	v_pk_mul_f32 v[8:9], v[8:9], v[12:13]
	v_pk_fma_f32 v[20:21], v[4:5], v[12:13], v[20:21]
	v_pk_fma_f32 v[4:5], v[4:5], v[16:17], v[8:9] neg_lo:[0,0,1] neg_hi:[0,0,1]
	v_lshlrev_b32_e32 v8, 16, v15
	v_and_b32_e32 v9, 0xffff0000, v15
	v_cvt_pk_bf16_f32 v176, v4, v5
	v_lshlrev_b32_e32 v4, 16, v19
	v_and_b32_e32 v5, 0xffff0000, v19
	v_pk_mul_f32 v[12:13], v[10:11], v[8:9]
	v_mov_b32_e32 v16, v3
	v_pk_fma_f32 v[12:13], v[6:7], v[4:5], v[12:13] neg_lo:[0,0,1] neg_hi:[0,0,1]
	v_pk_mul_f32 v[4:5], v[10:11], v[4:5]
	v_mov_b32_e32 v17, v3
	v_pk_fma_f32 v[4:5], v[6:7], v[8:9], v[4:5]
	v_cvt_pk_bf16_f32 v170, v32, v33
	v_cvt_pk_bf16_f32 v172, v20, v21
	v_cvt_pk_bf16_f32 v177, v12, v13
	v_cvt_pk_bf16_f32 v173, v4, v5
	s_add_u32 s56, s54, s64
	v_mov_b32_e32 v2, v3
	v_mov_b32_e32 v4, v3
	v_mov_b32_e32 v5, v3
	v_mov_b32_e32 v6, v3
	v_mov_b32_e32 v7, v3
	v_mov_b32_e32 v8, v3
	v_mov_b32_e32 v9, v3
	v_mov_b32_e32 v10, v3
	v_mov_b32_e32 v11, v3
	v_mov_b32_e32 v12, v3
	v_mov_b32_e32 v13, v3
	v_mov_b32_e32 v14, v3
	v_mov_b32_e32 v15, v3
	v_mov_b32_e32 v199, 0
	v_mov_b32_e32 v198, 0xf149f2ca
	v_mov_b64_e32 v[32:33], v[16:17]
	v_mov_b64_e32 v[48:49], v[16:17]
	v_mov_b64_e32 v[64:65], v[16:17]
	v_mov_b64_e32 v[80:81], v[16:17]
	s_addc_u32 s57, s55, 0
	v_lshl_add_u64 v[194:195], v[184:185], 0, vcc
	v_lshl_add_u64 v[196:197], v[186:187], 0, vcc
	v_or_b32_e32 v192, s62, v202
	s_mov_b32 s66, 0
	s_mov_b32 s67, 0
	v_mov_b64_e32 v[30:31], v[14:15]
	v_mov_b64_e32 v[28:29], v[12:13]
	v_mov_b64_e32 v[26:27], v[10:11]
	v_mov_b64_e32 v[24:25], v[8:9]
	v_mov_b64_e32 v[22:23], v[6:7]
	v_mov_b64_e32 v[20:21], v[4:5]
	v_mov_b64_e32 v[18:19], v[2:3]
	v_mov_b64_e32 v[46:47], v[14:15]
	v_mov_b64_e32 v[44:45], v[12:13]
	v_mov_b64_e32 v[42:43], v[10:11]
	v_mov_b64_e32 v[40:41], v[8:9]
	v_mov_b64_e32 v[38:39], v[6:7]
	v_mov_b64_e32 v[36:37], v[4:5]
	v_mov_b64_e32 v[34:35], v[2:3]
	v_mov_b64_e32 v[62:63], v[14:15]
	v_mov_b64_e32 v[60:61], v[12:13]
	v_mov_b64_e32 v[58:59], v[10:11]
	v_mov_b64_e32 v[56:57], v[8:9]
	v_mov_b64_e32 v[54:55], v[6:7]
	v_mov_b64_e32 v[52:53], v[4:5]
	v_mov_b64_e32 v[50:51], v[2:3]
	v_mov_b64_e32 v[78:79], v[14:15]
	v_mov_b64_e32 v[76:77], v[12:13]
	v_mov_b64_e32 v[74:75], v[10:11]
	v_mov_b64_e32 v[72:73], v[8:9]
	v_mov_b64_e32 v[70:71], v[6:7]
	v_mov_b64_e32 v[68:69], v[4:5]
	v_mov_b64_e32 v[66:67], v[2:3]
	v_mov_b32_e32 v16, v198
	v_mov_b32_e32 v17, v199
	s_branch .LBB0_673

; #define LAS __attribute__((address_space(3)))
; DI int tsw(int row) { return ((row >> 4) & 3) << 3; }
; template <class F> DI void load_v(u32x4 (&vr)[8], int lane, F vrow) {
; #pragma unroll
;     for (int it = 0; it < 8; ++it) { const int id = it * 64 + lane, key = id >> 3, part = id & 7; vr[it] = *(const u32x4*)(vrow(key) + 8 * part); }
; }
; DI void put_vt(LAS bf16_t* Vt, int lane, const u32x4 (&vr)[8]) {
; #pragma unroll
;     for (int it = 0; it < 8; ++it) { const int id = it * 64 + lane, key = id >> 3, part = id & 7; const u32x4 w = vr[it];
; #pragma unroll
;         for (int j = 0; j < 4; ++j) { const int d0 = 8 * part + 2 * j, ks_ = key ^ tsw(d0); Vt[d0 * TLD + ks_] = (bf16_t)(w[j] & 0xffffu); Vt[(d0 + 1) * TLD + ks_] = (bf16_t)(w[j] >> 16); } }
; }
; DI void dil_wave_unit(KArgs args, LAS unsigned char* L, const Ctx& c, int u, int lane, int wave) {
;     ...
;     for (int kt = 0; kt < 3; ++kt) { const int kj = jb - 1 + kt;
;         if (kj < 0 || kj >= nb) continue;
;         u32x4 vr[8]; bf16x8 kfa[2][4];
;         load_v(vr, lane, [&](int key) { return PROJ + (sb + cls + (size_t)dd * (64 * kj + key)) * NPROJ + C_VD + 64 * head; });
; #pragma unroll
;         for (int mt = 0; mt < 2; ++mt) { const int pos = cls + dd * (64 * kj + 32 * mt + rr);
; #pragma unroll
;             for (int ks = 0; ks < 4; ++ks) kfa[mt][ks] = *(const bf16x8*)(PROJ + (sb + pos) * NPROJ + C_KD + 64 * head + 16 * ks + 8 * hh); }
;         __builtin_amdgcn_sched_barrier(0);
;         asm volatile("s_waitcnt lgkmcnt(0)" ::: "memory");
;         put_vt(Vt, lane, vr);
.LBB0_673:
	s_add_i32 s58, s65, s67
	s_cmp_ge_u32 s58, s63
	s_cbranch_scc1 .LBB0_677
	v_add_u32_e32 v6, s66, v192
	v_subrev_u32_e32 v2, 64, v6
	v_lshlrev_b64 v[4:5], s33, v[2:3]
	v_lshl_add_u64 v[4:5], v[4:5], 0, s[56:57]
	v_mad_u64_u32 v[102:103], s[58:59], v4, s90, v[194:195]
	v_mov_b32_e32 v2, v103
	v_mad_u64_u32 v[4:5], s[58:59], v5, s90, v[2:3]
	v_subrev_u32_e32 v2, 56, v6
	v_mov_b32_e32 v103, v4
	v_lshlrev_b64 v[4:5], s33, v[2:3]
	v_lshl_add_u64 v[4:5], v[4:5], 0, s[56:57]
	v_mad_u64_u32 v[106:107], s[58:59], v4, s90, v[194:195]
	v_mov_b32_e32 v2, v107
	v_mad_u64_u32 v[4:5], s[58:59], v5, s90, v[2:3]
	v_subrev_u32_e32 v2, 48, v6
	v_mov_b32_e32 v107, v4
	v_lshlrev_b64 v[4:5], s33, v[2:3]
	v_lshl_add_u64 v[4:5], v[4:5], 0, s[56:57]
	v_mad_u64_u32 v[110:111], s[58:59], v4, s90, v[194:195]
	v_mov_b32_e32 v2, v111
	v_mad_u64_u32 v[4:5], s[58:59], v5, s90, v[2:3]
	v_subrev_u32_e32 v2, 40, v6
	v_mov_b32_e32 v111, v4
	v_lshlrev_b64 v[4:5], s33, v[2:3]
	v_lshl_add_u64 v[4:5], v[4:5], 0, s[56:57]
	v_mad_u64_u32 v[114:115], s[58:59], v4, s90, v[194:195]
	v_mov_b32_e32 v2, v115
	v_mad_u64_u32 v[4:5], s[58:59], v5, s90, v[2:3]
	v_subrev_u32_e32 v2, 32, v6
	v_mov_b32_e32 v115, v4
	v_lshlrev_b64 v[4:5], s33, v[2:3]
	v_lshl_add_u64 v[4:5], v[4:5], 0, s[56:57]
	v_mad_u64_u32 v[118:119], s[58:59], v4, s90, v[194:195]
	v_mov_b32_e32 v2, v119
	v_mad_u64_u32 v[4:5], s[58:59], v5, s90, v[2:3]
	v_subrev_u32_e32 v2, 24, v6
	v_mov_b32_e32 v119, v4
	v_lshlrev_b64 v[4:5], s33, v[2:3]
	v_lshl_add_u64 v[4:5], v[4:5], 0, s[56:57]
	v_mad_u64_u32 v[122:123], s[58:59], v4, s90, v[194:195]
	v_mov_b32_e32 v2, v123
	v_mad_u64_u32 v[4:5], s[58:59], v5, s90, v[2:3]
	v_add_u32_e32 v2, -16, v6
	v_mov_b32_e32 v123, v4
	v_lshlrev_b64 v[4:5], s33, v[2:3]
	v_lshl_add_u64 v[4:5], v[4:5], 0, s[56:57]
	v_mad_u64_u32 v[126:127], s[58:59], v4, s90, v[194:195]
	v_mov_b32_e32 v2, v127
	v_mad_u64_u32 v[4:5], s[58:59], v5, s90, v[2:3]
	v_add_u32_e32 v2, -8, v6
	v_mov_b32_e32 v127, v4
	v_lshlrev_b64 v[4:5], s33, v[2:3]
	v_lshl_add_u64 v[4:5], v[4:5], 0, s[56:57]
	v_mad_u64_u32 v[130:131], s[58:59], v4, s90, v[194:195]
	v_mov_b32_e32 v2, v131
	v_add_u32_e32 v8, s66, v191
	v_mad_u64_u32 v[4:5], s[58:59], v5, s90, v[2:3]
	v_subrev_u32_e32 v2, 64, v8
	v_lshlrev_b32_e32 v2, s33, v2
	v_add_u32_e32 v2, s64, v2
	v_mov_b32_e32 v131, v4
	v_lshl_add_u64 v[4:5], s[54:55], 0, v[2:3]
	v_mad_u64_u32 v[6:7], s[58:59], v4, s90, v[196:197]
	v_subrev_u32_e32 v4, 32, v8
	v_lshlrev_b32_e32 v4, s33, v4
	v_add_u32_e32 v200, s64, v4
	v_mov_b32_e32 v201, v3
	v_mad_u32_u24 v7, v5, s90, v7
	v_lshl_add_u64 v[4:5], s[54:55], 0, v[200:201]
	v_mad_u64_u32 v[8:9], s[58:59], v4, s90, v[196:197]
	v_mad_u32_u24 v9, v5, s90, v9
	global_load_dwordx4 v[94:97], v[6:7], off offset:2304
	global_load_dwordx4 v[82:85], v[6:7], off offset:2336
	global_load_dwordx4 v[90:93], v[6:7], off offset:2368
	global_load_dwordx4 v[86:89], v[6:7], off offset:2400
	global_load_dwordx4 v[98:101], v[8:9], off offset:2304
	s_nop 0
	global_load_dwordx4 v[4:7], v[8:9], off offset:2336
	global_load_dwordx4 v[12:15], v[8:9], off offset:2368
	global_load_dwordx4 v[8:11], v[8:9], off offset:2400
	global_load_dwordx4 v[102:105], v[102:103], off offset:3072
	global_load_dwordx4 v[106:109], v[106:107], off offset:3072
	global_load_dwordx4 v[110:113], v[110:111], off offset:3072
	global_load_dwordx4 v[114:117], v[114:115], off offset:3072
	global_load_dwordx4 v[118:121], v[118:119], off offset:3072
	global_load_dwordx4 v[122:125], v[122:123], off offset:3072
	global_load_dwordx4 v[126:129], v[126:127], off offset:3072
	global_load_dwordx4 v[130:133], v[130:131], off offset:3072
	s_waitcnt lgkmcnt(0)
	s_waitcnt vmcnt(7)
	ds_write_b16 v228, v102
	ds_write_b16_d16_hi v228, v102 offset:144
	ds_write_b16 v228, v103 offset:288
	ds_write_b16_d16_hi v228, v103 offset:432
	ds_write_b16 v228, v104 offset:576
	ds_write_b16_d16_hi v228, v104 offset:720
	ds_write_b16 v228, v105 offset:864
	ds_write_b16_d16_hi v228, v105 offset:1008
	s_waitcnt vmcnt(6)
	ds_write_b16 v229, v106
	ds_write_b16_d16_hi v229, v106 offset:144
	ds_write_b16 v229, v107 offset:288
	ds_write_b16_d16_hi v229, v107 offset:432
	ds_write_b16 v229, v108 offset:576
	ds_write_b16_d16_hi v229, v108 offset:720
	ds_write_b16 v229, v109 offset:864
	ds_write_b16_d16_hi v229, v109 offset:1008
	s_waitcnt vmcnt(5)
	ds_write_b16 v230, v110
	ds_write_b16_d16_hi v230, v110 offset:144
	ds_write_b16 v230, v111 offset:288
	ds_write_b16_d16_hi v230, v111 offset:432
	ds_write_b16 v230, v112 offset:576
	ds_write_b16_d16_hi v230, v112 offset:720
	ds_write_b16 v230, v113 offset:864
	ds_write_b16_d16_hi v230, v113 offset:1008
	s_waitcnt vmcnt(4)
	ds_write_b16 v231, v114
	ds_write_b16_d16_hi v231, v114 offset:144
	ds_write_b16 v231, v115 offset:288
	ds_write_b16_d16_hi v231, v115 offset:432
	ds_write_b16 v231, v116 offset:576
	ds_write_b16_d16_hi v231, v116 offset:720
	ds_write_b16 v231, v117 offset:864
	ds_write_b16_d16_hi v231, v117 offset:1008
	s_waitcnt vmcnt(3)
	ds_write_b16 v228, v118 offset:64
	ds_write_b16_d16_hi v228, v118 offset:208
	ds_write_b16 v228, v119 offset:352
	ds_write_b16_d16_hi v228, v119 offset:496
	ds_write_b16 v228, v120 offset:640
	ds_write_b16_d16_hi v228, v120 offset:784
	ds_write_b16 v228, v121 offset:928
	ds_write_b16_d16_hi v228, v121 offset:1072
	s_waitcnt vmcnt(2)
	ds_write_b16 v232, v122
	ds_write_b16_d16_hi v232, v122 offset:144
	ds_write_b16 v232, v123 offset:288
	ds_write_b16_d16_hi v232, v123 offset:432
	ds_write_b16 v232, v124 offset:576
	ds_write_b16_d16_hi v232, v124 offset:720
	ds_write_b16 v232, v125 offset:864
	ds_write_b16_d16_hi v232, v125 offset:1008
	s_waitcnt vmcnt(1)
; DI unsigned pk2(float lo, float hi) { f32x2 v = {lo, hi}; bf16x2v b = __builtin_convertvector(v, bf16x2v); return __builtin_bit_cast(unsigned, b); }
; DI float bflo(unsigned u) { return __uint_as_float(u << 16); }
; DI float bfhi(unsigned u) { return __uint_as_float(u & 0xffff0000u); }
; #define MFMA32(a, b, c) __builtin_amdgcn_mfma_f32_32x32x16_bf16((a), (b), (c), 0, 0, 0)
; DI void put_vt(LAS bf16_t* Vt, int lane, const u32x4 (&vr)[8]) {
;     ...
;         for (int j = 0; j < 4; ++j) { const int d0 = 8 * part + 2 * j, ks_ = key ^ tsw(d0); Vt[d0 * TLD + ks_] = (bf16_t)(w[j] & 0xffffu); Vt[(d0 + 1) * TLD + ks_] = (bf16_t)(w[j] >> 16); } }
; DI void rope_load(RopeCS& t, const float* cs, int hh) {
; #pragma unroll
;     for (int ks = 0; ks < 2; ++ks) { const float* cp = cs + 16 * ks + 8 * hh; t.v[ks][0] = *(const f32x4*)cp; t.v[ks][1] = *(const f32x4*)(cp + 4); t.v[ks][2] = *(const f32x4*)(cp + 32); t.v[ks][3] = *(const f32x4*)(cp + 36); }
; }
; DI void rope_frag4(bf16x8 (&f)[4], const RopeCS& t) {
; #pragma unroll
;     for (int ks = 0; ks < 2; ++ks) {
;         const f32x4 c0 = t.v[ks][0], c1 = t.v[ks][1], s0 = t.v[ks][2], s1 = t.v[ks][3];
;         const u32x4 a = __builtin_bit_cast(u32x4, f[ks]), b = __builtin_bit_cast(u32x4, f[ks + 2]); u32x4 ra, rb;
; #pragma unroll
;         for (int j = 0; j < 4; ++j) { const float cl = (j < 2) ? c0[2 * j] : c1[2 * j - 4], ch = (j < 2) ? c0[2 * j + 1] : c1[2 * j - 3];
;             const float sl = (j < 2) ? s0[2 * j] : s1[2 * j - 4], sh = (j < 2) ? s0[2 * j + 1] : s1[2 * j - 3];
;             const float x1l = bflo(a[j]), x1h = bfhi(a[j]), x2l = bflo(b[j]), x2h = bfhi(b[j]);
;             ra[j] = pk2(x1l * cl - x2l * sl, x1h * ch - x2h * sh); rb[j] = pk2(x1l * sl + x2l * cl, x1h * sh + x2h * ch); }
;         f[ks] = __builtin_bit_cast(bf16x8, ra); f[ks + 2] = __builtin_bit_cast(bf16x8, rb); }
; DI void dil_wave_unit(KArgs args, LAS unsigned char* L, const Ctx& c, int u, int lane, int wave) {
;     ...
;         for (int mt = 0; mt < 2; ++mt) {
;             RopeCS tk; rope_load(tk, CS + (size_t)(cls + dd * (64 * kj + 32 * mt + rr)) * 64, hh); __builtin_amdgcn_sched_barrier(0);
;             rope_frag4(kfa[mt], tk);
; #pragma unroll
;             for (int ks = 0; ks < 4; ++ks) { acc[mt][0] = MFMA32(kfa[mt][ks], qf[0][ks], acc[mt][0]); acc[mt][1] = MFMA32(kfa[mt][ks], qf[1][ks], acc[mt][1]); } }
	ds_write_b16 v233, v126
	ds_write_b16_d16_hi v233, v126 offset:144
	ds_write_b16 v233, v127 offset:288
	ds_write_b16_d16_hi v233, v127 offset:432
	ds_write_b16 v233, v128 offset:576
	ds_write_b16_d16_hi v233, v128 offset:720
	ds_write_b16 v233, v129 offset:864
	ds_write_b16_d16_hi v233, v129 offset:1008
	s_waitcnt vmcnt(0)
	ds_write_b16 v234, v130
	ds_write_b16_d16_hi v234, v130 offset:144
	ds_write_b16 v234, v131 offset:288
	ds_write_b16_d16_hi v234, v131 offset:432
	ds_write_b16 v234, v132 offset:576
	ds_write_b16_d16_hi v234, v132 offset:720
	ds_write_b16 v234, v133 offset:864
	ds_write_b16_d16_hi v234, v133 offset:1008
	v_lshlrev_b64 v[102:103], 8, v[2:3]
	v_lshl_add_u64 v[114:115], v[182:183], 0, v[102:103]
	global_load_dwordx4 v[120:123], v[114:115], off offset:16
	global_load_dwordx4 v[128:131], v[114:115], off
	global_load_dwordx4 v[124:127], v[114:115], off offset:144
	global_load_dwordx4 v[132:135], v[114:115], off offset:128
	global_load_dwordx4 v[102:105], v[114:115], off offset:80
	global_load_dwordx4 v[110:113], v[114:115], off offset:64
	global_load_dwordx4 v[106:109], v[114:115], off offset:208
	global_load_dwordx4 v[114:117], v[114:115], off offset:192
	v_lshlrev_b32_e32 v136, 16, v90
	v_and_b32_e32 v137, 0xffff0000, v90
	v_lshlrev_b32_e32 v118, 16, v94
	v_and_b32_e32 v119, 0xffff0000, v94
	s_waitcnt vmcnt(4)
	v_pk_mul_f32 v[138:139], v[132:133], v[136:137]
	v_lshlrev_b32_e32 v94, 16, v95
	v_pk_fma_f32 v[138:139], v[128:129], v[118:119], v[138:139] neg_lo:[0,0,1] neg_hi:[0,0,1]
	v_pk_mul_f32 v[118:119], v[132:133], v[118:119]
	v_and_b32_e32 v95, 0xffff0000, v95
	v_pk_fma_f32 v[118:119], v[128:129], v[136:137], v[118:119]
	v_lshlrev_b32_e32 v128, 16, v91
	v_and_b32_e32 v129, 0xffff0000, v91
	v_pk_mul_f32 v[132:133], v[134:135], v[128:129]
	v_cvt_pk_bf16_f32 v118, v118, v119
	v_pk_fma_f32 v[132:133], v[130:131], v[94:95], v[132:133] neg_lo:[0,0,1] neg_hi:[0,0,1]
	v_pk_mul_f32 v[94:95], v[134:135], v[94:95]
	v_cvt_pk_bf16_f32 v90, v138, v139
	v_pk_fma_f32 v[94:95], v[130:131], v[128:129], v[94:95]
	v_lshlrev_b32_e32 v128, 16, v92
	v_and_b32_e32 v129, 0xffff0000, v92
	v_cvt_pk_bf16_f32 v119, v94, v95
	v_lshlrev_b32_e32 v94, 16, v96
	v_and_b32_e32 v95, 0xffff0000, v96
	v_pk_mul_f32 v[130:131], v[124:125], v[128:129]
	v_lshlrev_b32_e32 v96, 16, v93
	v_pk_fma_f32 v[130:131], v[120:121], v[94:95], v[130:131] neg_lo:[0,0,1] neg_hi:[0,0,1]
	v_pk_mul_f32 v[94:95], v[124:125], v[94:95]
	v_cvt_pk_bf16_f32 v91, v132, v133
	v_pk_fma_f32 v[94:95], v[120:121], v[128:129], v[94:95]
	v_cvt_pk_bf16_f32 v92, v130, v131
	v_cvt_pk_bf16_f32 v120, v94, v95
	v_lshlrev_b32_e32 v94, 16, v97
	v_and_b32_e32 v95, 0xffff0000, v97
	v_and_b32_e32 v97, 0xffff0000, v93
	v_pk_mul_f32 v[124:125], v[126:127], v[96:97]
	s_nop 0
	v_pk_fma_f32 v[124:125], v[122:123], v[94:95], v[124:125] neg_lo:[0,0,1] neg_hi:[0,0,1]
	v_pk_mul_f32 v[94:95], v[126:127], v[94:95]
	v_cvt_pk_bf16_f32 v93, v124, v125
	v_pk_fma_f32 v[94:95], v[122:123], v[96:97], v[94:95]
	v_lshlrev_b32_e32 v96, 16, v82
	v_and_b32_e32 v97, 0xffff0000, v82
	v_cvt_pk_bf16_f32 v121, v94, v95
	v_lshlrev_b32_e32 v94, 16, v86
	v_and_b32_e32 v95, 0xffff0000, v86
	s_waitcnt vmcnt(0)
	v_pk_mul_f32 v[122:123], v[114:115], v[96:97]
	v_lshlrev_b32_e32 v82, 16, v83
	v_pk_fma_f32 v[122:123], v[110:111], v[94:95], v[122:123]
	v_pk_mul_f32 v[94:95], v[114:115], v[94:95]
	v_and_b32_e32 v83, 0xffff0000, v83
	v_pk_fma_f32 v[94:95], v[110:111], v[96:97], v[94:95] neg_lo:[0,0,1] neg_hi:[0,0,1]
	v_lshlrev_b32_e32 v86, 16, v87
	v_cvt_pk_bf16_f32 v110, v94, v95
	v_and_b32_e32 v87, 0xffff0000, v87
	v_pk_mul_f32 v[94:95], v[116:117], v[82:83]
	v_cvt_pk_bf16_f32 v122, v122, v123
	v_pk_fma_f32 v[94:95], v[112:113], v[86:87], v[94:95]
	v_pk_mul_f32 v[86:87], v[116:117], v[86:87]
	v_cvt_pk_bf16_f32 v123, v94, v95
	v_pk_fma_f32 v[82:83], v[112:113], v[82:83], v[86:87] neg_lo:[0,0,1] neg_hi:[0,0,1]
	v_lshlrev_b32_e32 v86, 16, v84
	v_and_b32_e32 v87, 0xffff0000, v84
	v_cvt_pk_bf16_f32 v111, v82, v83
	v_lshlrev_b32_e32 v82, 16, v88
	v_and_b32_e32 v83, 0xffff0000, v88
	v_pk_mul_f32 v[94:95], v[106:107], v[86:87]
	v_lshlrev_b32_e32 v84, 16, v89
	v_pk_fma_f32 v[94:95], v[102:103], v[82:83], v[94:95]
	v_pk_mul_f32 v[82:83], v[106:107], v[82:83]
	v_cvt_pk_bf16_f32 v124, v94, v95
	v_pk_fma_f32 v[82:83], v[102:103], v[86:87], v[82:83] neg_lo:[0,0,1] neg_hi:[0,0,1]
	v_mfma_f32_32x32x16_bf16 v[130:145], v[90:93], v[146:149], 0
	v_cvt_pk_bf16_f32 v112, v82, v83
	v_lshlrev_b32_e32 v82, 16, v85
	v_and_b32_e32 v83, 0xffff0000, v85
	v_and_b32_e32 v85, 0xffff0000, v89
	v_mul_f32_e64 v86, v108, v84
	v_mul_f32_e64 v87, v109, v85
	v_lshlrev_b64 v[102:103], 8, v[200:201]
	v_pk_fma_f32 v[86:87], v[104:105], v[82:83], v[86:87] neg_lo:[0,0,1] neg_hi:[0,0,1]
	v_pk_mul_f32 v[82:83], v[108:109], v[82:83]
	v_cvt_pk_bf16_f32 v113, v86, v87
	v_pk_fma_f32 v[82:83], v[104:105], v[84:85], v[82:83]
	v_lshl_add_u64 v[114:115], v[182:183], 0, v[102:103]
	v_cvt_pk_bf16_f32 v125, v82, v83
	v_mfma_f32_32x32x16_bf16 v[82:97], v[90:93], v[162:165], 0
	v_mfma_f32_32x32x16_bf16 v[130:145], v[110:113], v[158:161], v[130:145]
	v_mfma_f32_32x32x16_bf16 v[82:97], v[110:113], v[174:177], v[82:97]
	v_mfma_f32_32x32x16_bf16 v[130:145], v[118:121], v[150:153], v[130:145]
	v_mfma_f32_32x32x16_bf16 v[82:97], v[118:121], v[166:169], v[82:97]
	v_mfma_f32_32x32x16_bf16 v[130:145], v[122:125], v[154:157], v[130:145]
	v_mfma_f32_32x32x16_bf16 v[82:97], v[122:125], v[170:173], v[82:97]
	global_load_dwordx4 v[102:105], v[114:115], off offset:16
	global_load_dwordx4 v[106:109], v[114:115], off
	global_load_dwordx4 v[110:113], v[114:115], off offset:144
	global_load_dwordx4 v[116:119], v[114:115], off offset:128
	global_load_dwordx4 v[120:123], v[114:115], off offset:80
	global_load_dwordx4 v[124:127], v[114:115], off offset:64
	global_load_dwordx4 v[216:219], v[114:115], off offset:208
	global_load_dwordx4 v[204:207], v[114:115], off offset:192
	v_lshlrev_b32_e32 v128, 16, v98
	v_and_b32_e32 v129, 0xffff0000, v98
	v_lshlrev_b32_e32 v200, 16, v12
	v_and_b32_e32 v201, 0xffff0000, v12
	s_waitcnt vmcnt(4)
; #define MFMA32(a, b, c) __builtin_amdgcn_mfma_f32_32x32x16_bf16((a), (b), (c), 0, 0, 0)
; DI int crow(int reg, int h) { return (reg & 3) + 8 * (reg >> 2) + 4 * h; }
; DI void dil_wave_unit(KArgs args, LAS unsigned char* L, const Ctx& c, int u, int lane, int wave) {
;     ...
;         for (int mt = 0; mt < 2; ++mt) {
;             RopeCS tk; rope_load(tk, CS + (size_t)(cls + dd * (64 * kj + 32 * mt + rr)) * 64, hh); __builtin_amdgcn_sched_barrier(0);
;             rope_frag4(kfa[mt], tk);
; #pragma unroll
;             for (int ks = 0; ks < 4; ++ks) { acc[mt][0] = MFMA32(kfa[mt][ks], qf[0][ks], acc[mt][0]); acc[mt][1] = MFMA32(kfa[mt][ks], qf[1][ks], acc[mt][1]); } }
; #pragma unroll
;         for (int nt = 0; nt < 2; ++nt) { const int qc = 32 * nt + rr;
; #pragma unroll
;             for (int mt = 0; mt < 2; ++mt)
; #pragma unroll
;                 for (int gg = 0; gg < 16; ++gg) { const int kc = 32 * mt + crow(gg, hh); const bool ok = (kt == 1) || (kt == 0 ? (kc >= qc) : (kc <= qc));
	v_pk_mul_f32 v[114:115], v[116:117], v[200:201]
	v_pk_mul_f32 v[116:117], v[116:117], v[128:129]
	v_pk_fma_f32 v[114:115], v[106:107], v[128:129], v[114:115] neg_lo:[0,0,1] neg_hi:[0,0,1]
	v_pk_fma_f32 v[106:107], v[106:107], v[200:201], v[116:117]
	v_lshlrev_b32_e32 v98, 16, v99
	v_cvt_pk_bf16_f32 v12, v106, v107
	v_lshlrev_b32_e32 v106, 16, v13
	v_and_b32_e32 v107, 0xffff0000, v13
	v_and_b32_e32 v99, 0xffff0000, v99
	v_pk_mul_f32 v[116:117], v[118:119], v[106:107]
	v_cvt_pk_bf16_f32 v114, v114, v115
	v_pk_fma_f32 v[116:117], v[108:109], v[98:99], v[116:117] neg_lo:[0,0,1] neg_hi:[0,0,1]
	v_pk_mul_f32 v[98:99], v[118:119], v[98:99]
	v_cvt_pk_bf16_f32 v115, v116, v117
	v_pk_fma_f32 v[98:99], v[108:109], v[106:107], v[98:99]
	v_lshlrev_b32_e32 v106, 16, v14
	v_and_b32_e32 v107, 0xffff0000, v14
	v_cvt_pk_bf16_f32 v13, v98, v99
	v_lshlrev_b32_e32 v98, 16, v100
	v_and_b32_e32 v99, 0xffff0000, v100
	v_pk_mul_f32 v[108:109], v[110:111], v[106:107]
	v_lshlrev_b32_e32 v100, 16, v15
	v_pk_fma_f32 v[108:109], v[102:103], v[98:99], v[108:109] neg_lo:[0,0,1] neg_hi:[0,0,1]
	v_pk_mul_f32 v[98:99], v[110:111], v[98:99]
	v_cvt_pk_bf16_f32 v116, v108, v109
	v_pk_fma_f32 v[98:99], v[102:103], v[106:107], v[98:99]
	s_cmp_lt_i32 s67, 1
	v_cvt_pk_bf16_f32 v14, v98, v99
	v_lshlrev_b32_e32 v98, 16, v101
	v_and_b32_e32 v99, 0xffff0000, v101
	v_and_b32_e32 v101, 0xffff0000, v15
	v_pk_mul_f32 v[102:103], v[112:113], v[100:101]
	s_nop 0
	v_pk_fma_f32 v[102:103], v[104:105], v[98:99], v[102:103] neg_lo:[0,0,1] neg_hi:[0,0,1]
	v_pk_mul_f32 v[98:99], v[112:113], v[98:99]
	v_cvt_pk_bf16_f32 v117, v102, v103
	v_pk_fma_f32 v[98:99], v[104:105], v[100:101], v[98:99]
	v_lshlrev_b32_e32 v100, 16, v4
	v_and_b32_e32 v101, 0xffff0000, v4
	v_cvt_pk_bf16_f32 v15, v98, v99
	v_lshlrev_b32_e32 v98, 16, v8
	v_and_b32_e32 v99, 0xffff0000, v8
	s_waitcnt vmcnt(0)
	v_pk_mul_f32 v[102:103], v[204:205], v[100:101]
	s_nop 0
	v_pk_fma_f32 v[102:103], v[124:125], v[98:99], v[102:103]
	v_pk_mul_f32 v[98:99], v[204:205], v[98:99]
	v_cvt_pk_bf16_f32 v4, v102, v103
	v_pk_fma_f32 v[98:99], v[124:125], v[100:101], v[98:99] neg_lo:[0,0,1] neg_hi:[0,0,1]
	v_lshlrev_b32_e32 v100, 16, v5
	v_and_b32_e32 v101, 0xffff0000, v5
	v_cvt_pk_bf16_f32 v8, v98, v99
	v_lshlrev_b32_e32 v98, 16, v9
	v_and_b32_e32 v99, 0xffff0000, v9
	v_pk_mul_f32 v[102:103], v[206:207], v[100:101]
	s_nop 0
	v_pk_fma_f32 v[102:103], v[126:127], v[98:99], v[102:103]
	v_pk_mul_f32 v[98:99], v[206:207], v[98:99]
	v_cvt_pk_bf16_f32 v5, v102, v103
	v_pk_fma_f32 v[98:99], v[126:127], v[100:101], v[98:99] neg_lo:[0,0,1] neg_hi:[0,0,1]
	v_lshlrev_b32_e32 v100, 16, v6
	v_and_b32_e32 v101, 0xffff0000, v6
	v_cvt_pk_bf16_f32 v9, v98, v99
	v_lshlrev_b32_e32 v98, 16, v10
	v_and_b32_e32 v99, 0xffff0000, v10
	v_pk_mul_f32 v[102:103], v[216:217], v[100:101]
	s_nop 0
	v_pk_fma_f32 v[102:103], v[120:121], v[98:99], v[102:103]
	v_pk_mul_f32 v[98:99], v[216:217], v[98:99]
	v_cvt_pk_bf16_f32 v6, v102, v103
	v_pk_fma_f32 v[98:99], v[120:121], v[100:101], v[98:99] neg_lo:[0,0,1] neg_hi:[0,0,1]
	v_lshlrev_b32_e32 v100, 16, v11
	v_and_b32_e32 v101, 0xffff0000, v11
	v_cvt_pk_bf16_f32 v10, v98, v99
	v_lshlrev_b32_e32 v98, 16, v7
	v_and_b32_e32 v99, 0xffff0000, v7
	v_pk_mul_f32 v[102:103], v[218:219], v[100:101]
	s_nop 0
	v_pk_fma_f32 v[102:103], v[122:123], v[98:99], v[102:103] neg_lo:[0,0,1] neg_hi:[0,0,1]
	v_pk_mul_f32 v[98:99], v[218:219], v[98:99]
	v_cvt_pk_bf16_f32 v11, v102, v103
	v_pk_fma_f32 v[98:99], v[122:123], v[100:101], v[98:99]
	s_nop 0
	v_cvt_pk_bf16_f32 v7, v98, v99
	v_mfma_f32_32x32x16_bf16 v[98:113], v[114:117], v[146:149], 0
	v_mfma_f32_32x32x16_bf16 v[114:129], v[114:117], v[162:165], 0
	v_mfma_f32_32x32x16_bf16 v[98:113], v[8:11], v[158:161], v[98:113]
	v_mfma_f32_32x32x16_bf16 v[114:129], v[8:11], v[174:177], v[114:129]
	v_mfma_f32_32x32x16_bf16 v[98:113], v[12:15], v[150:153], v[98:113]
	v_mfma_f32_32x32x16_bf16 v[114:129], v[12:15], v[166:169], v[114:129]
	v_mfma_f32_32x32x16_bf16 v[98:113], v[4:7], v[154:157], v[98:113]
	v_mfma_f32_32x32x16_bf16 v[114:129], v[4:7], v[170:173], v[114:129]
	s_cbranch_scc1 .LBB0_678
	s_cmp_lg_u32 s67, 1
	s_cbranch_scc0 .LBB0_679
	s_mov_b64 vcc, -1
	s_mov_b64 s[58:59], 0
	s_branch .LBB0_680
